# P5: one-dword-per-line cache-warming loads of the x tile during K-steps 6-9 (test)
# baseline (speedup 1.0000x reference)
;     ...
;   const int srow = tid >> 3, skc = tid & 7;
;   const u16* Ag = A + (size_t)(m0 + srow) * K + skc * 8;
;   const u16* Bg[4];
; #pragma unroll
;   for (int i = 0; i < 4; ++i) { int n = n0 + srow + 64 * i; n = n < nmax ? n : nmax - 1; Bg[i] = Bt + (size_t)n * K + skc * 8; }
;   const int nk = nk_override ? nk_override : K / 64;
; #pragma unroll
;   for (int i = 0; i < 4; ++i) { ra[i] = *(const u32x4*)(Ag + (size_t)(64 * i) * K); rb[i] = *(const u32x4*)(Bg[i]); }
; #pragma unroll
;   for (int i = 0; i < 4; ++i) { *(u32x4*)(As0 + (srow + 64 * i) * LD + skc * 8) = ra[i]; *(u32x4*)(Bs0 + (srow + 64 * i) * LD + skc * 8) = rb[i]; }
;   if (nk > 1) {
; #pragma unroll
;     for (int i = 0; i < 4; ++i) { ra[i] = *(const u32x4*)(Ag + (size_t)(64 * i) * K + 64); rb[i] = *(const u32x4*)(Bg[i] + 64); }
;   }
;   for (int kt = 0; kt < nk; ++kt) {
;     __syncthreads();
;     if (kt + 1 < nk) {
;       u16* aw = As0 + ((kt + 1) & 1) * 256 * LD;
;       u16* bw = Bs0 + ((kt + 1) & 1) * 256 * LD;
; #pragma unroll
;       for (int i = 0; i < 4; ++i) { *(u32x4*)(aw + (srow + 64 * i) * LD + skc * 8) = ra[i]; *(u32x4*)(bw + (srow + 64 * i) * LD + skc * 8) = rb[i]; }
;     }
;     if (kt + 2 < nk) {
; #pragma unroll
;       for (int i = 0; i < 4; ++i) { ra[i] = *(const u32x4*)(Ag + (size_t)(64 * i) * K + (kt + 2) * 64); rb[i] = *(const u32x4*)(Bg[i] + (kt + 2) * 64); }
;     }
;     __builtin_amdgcn_sched_barrier(0);
;     const u16* as = As0 + (kt & 1) * 256 * LD + (wr * 128 + l31) * LD + h * 8;
;     const u16* bs = Bs0 + (kt & 1) * 256 * LD + (wc * 64 + l31) * LD + h * 8;
; __device__ void phase_gemm2(const Params& p, char* lds, int bid, int nb, bool fused) {
;     ...
;         const int tok = m0 + wr * 128 + tt * 32 + l31;
;         const float* xr = p.x + (size_t)tok * DM + n0 + wc * 64;
.LBB0_554:
	s_ashr_i32 s4, s3, 31
	s_lshr_b32 s4, s4, 30
	s_add_i32 s4, s3, s4
	s_and_b32 s5, s4, 0xfffffc
	s_sub_i32 s5, s3, s5
	v_mov_b32_e32 v66, v223
	s_lshl_b32 s34, s5, 8
	s_lshl_b32 s4, s4, 6
	v_ashrrev_i32_e32 v40, 3, v66
	v_add_u32_e32 v8, s34, v40
	s_and_b32 s38, s4, 0xffffff00
	v_lshlrev_b32_e32 v4, 4, v66
	v_min_i32_e32 v6, 0x3ff, v8
	s_add_i32 s38, s38, s44
	v_and_b32_e32 v150, 0x70, v4
	v_ashrrev_i32_e32 v7, 31, v6
	v_add_u32_e32 v2, s38, v40
	s_waitcnt lgkmcnt(0)
	v_lshl_add_u64 v[4:5], s[22:23], 0, v[150:151]
	v_lshlrev_b64 v[6:7], 11, v[6:7]
	v_ashrrev_i32_e32 v3, 31, v2
	v_lshl_add_u64 v[130:131], v[4:5], 0, v[6:7]
	v_min_i32_e32 v6, 0x3bf, v8
	v_lshlrev_b64 v[2:3], 11, v[2:3]
	v_ashrrev_i32_e32 v7, 31, v6
	v_lshlrev_b64 v[6:7], 11, v[6:7]
	v_lshl_add_u64 v[2:3], s[16:17], 0, v[2:3]
	v_lshl_add_u64 v[34:35], v[4:5], 0, v[6:7]
	v_min_i32_e32 v6, 0x37f, v8
	v_lshl_add_u64 v[132:133], v[2:3], 0, v[150:151]
	v_ashrrev_i32_e32 v7, 31, v6
	v_add_co_u32_e32 v134, vcc, s45, v132
	v_lshlrev_b64 v[6:7], 11, v[6:7]
	s_nop 0
	v_addc_co_u32_e32 v135, vcc, 0, v133, vcc
	v_lshl_add_u64 v[36:37], v[4:5], 0, v[6:7]
	v_min_i32_e32 v6, 0x33f, v8
	v_add_co_u32_e32 v14, vcc, s45, v34
	v_ashrrev_i32_e32 v7, 31, v6
	s_nop 0
	v_addc_co_u32_e32 v15, vcc, 0, v35, vcc
	v_lshlrev_b64 v[6:7], 11, v[6:7]
	v_add_co_u32_e32 v136, vcc, s46, v132
	v_lshl_add_u64 v[38:39], v[4:5], 0, v[6:7]
	global_load_dwordx4 v[2:5], v[132:133], off
	global_load_dwordx4 v[6:9], v[130:131], off
	v_addc_co_u32_e32 v137, vcc, 0, v133, vcc
	v_add_co_u32_e32 v22, vcc, s46, v36
	global_load_dwordx4 v[10:13], v[134:135], off
	global_load_dwordx4 v[18:21], v[136:137], off
	v_addc_co_u32_e32 v23, vcc, 0, v37, vcc
	global_load_dwordx4 v[14:17], v[14:15], off
	v_add_co_u32_e32 v138, vcc, s47, v132
	global_load_dwordx4 v[22:25], v[22:23], off
	s_nop 0
	v_addc_co_u32_e32 v139, vcc, 0, v133, vcc
	v_add_co_u32_e32 v30, vcc, s47, v38
	global_load_dwordx4 v[26:29], v[138:139], off
	s_nop 0
	v_addc_co_u32_e32 v31, vcc, 0, v39, vcc
	global_load_dwordx4 v[30:33], v[30:31], off
	v_mul_lo_u32 v40, v40, s52
	v_add3_u32 v149, 0, v150, v40
	v_lshl_add_u64 v[144:145], v[38:39], 0, s[30:31]
	v_add3_u32 v152, s51, v150, v40
	v_lshl_add_u64 v[140:141], v[34:35], 0, s[26:27]
	v_lshl_add_u64 v[142:143], v[36:37], 0, s[28:29]
	global_load_dwordx4 v[34:37], v[132:133], off offset:128
	global_load_dwordx4 v[38:41], v[130:131], off offset:128
	global_load_dwordx4 v[42:45], v[134:135], off offset:128
	global_load_dwordx4 v[46:49], v[136:137], off offset:128
	global_load_dwordx4 v[50:53], v[140:141], off offset:128
	global_load_dwordx4 v[54:57], v[142:143], off offset:128
	global_load_dwordx4 v[58:61], v[138:139], off offset:128
	global_load_dwordx4 v[62:65], v[144:145], off offset:128
	v_readfirstlane_b32 s5, v66
	s_and_b32 s4, s5, 0xc0
	s_ashr_i32 s5, s5, 1
	v_and_b32_e32 v146, 31, v66
	s_and_b32 s5, s5, 0xffffff80
	v_bfe_u32 v159, v66, 5, 1
	v_lshlrev_b32_e32 v150, 4, v159
	s_waitcnt vmcnt(15)
	ds_write_b128 v149, v[2:5]
	s_waitcnt vmcnt(14)
	ds_write_b128 v152, v[6:9]
	s_waitcnt vmcnt(13)
	ds_write_b128 v149, v[10:13] offset:9216
	s_waitcnt vmcnt(11)
	ds_write_b128 v152, v[14:17] offset:9216
	ds_write_b128 v149, v[18:21] offset:18432
	s_waitcnt vmcnt(10)
	ds_write_b128 v152, v[22:25] offset:18432
	s_waitcnt vmcnt(9)
	ds_write_b128 v149, v[26:29] offset:27648
	s_waitcnt vmcnt(8)
	ds_write_b128 v152, v[30:33] offset:27648
	s_waitcnt lgkmcnt(0)
	s_barrier
	v_or_b32_e32 v2, s5, v146
	v_mul_lo_u32 v2, v2, s52
	v_add3_u32 v147, 0, v2, v150
	v_or_b32_e32 v2, s4, v146
	v_mul_u32_u24_e32 v2, 0x90, v2
	v_add3_u32 v148, s51, v2, v150
	v_lshrrev_b32_e32 v153, 3, v223
	v_lshlrev_b32_e32 v153, 11, v153
	v_lshlrev_b32_e32 v2, 4, v223
	v_and_b32_e32 v2, 0x70, v2
	v_or_b32_e32 v153, v153, v2
	s_lshl_b32 s53, s38, 11
	s_add_u32 s74, s16, s53
	s_addc_u32 s75, s17, 0
	s_add_u32 s76, s74, 0x20000
	s_addc_u32 s77, s75, 0
	s_add_u32 s78, s74, 0x40000
	s_addc_u32 s79, s75, 0
	s_add_u32 s80, s74, 0x60000
	s_addc_u32 s81, s75, 0
	s_lshl_b32 s53, s34, 11
	s_add_u32 s82, s22, s53
	s_addc_u32 s83, s23, 0
	s_add_u32 s84, s82, 0x20000
	s_addc_u32 s85, s83, 0
	s_add_u32 s86, s82, 0x40000
	s_addc_u32 s87, s83, 0
	s_add_u32 s92, s82, 0x60000
	s_addc_u32 s93, s83, 0
	v_lshrrev_b32_e32 v154, 1, v223
	v_lshlrev_b32_e32 v154, 12, v154
	v_and_b32_e32 v155, 1, v223
	v_lshl_or_b32 v154, v155, 9, v154
	s_lshl_b32 s53, s38, 12
	s_add_u32 s94, s24, s53
	s_addc_u32 s95, s25, 0
	s_lshl_b32 s53, s34, 2
	s_add_u32 s94, s94, s53
	s_addc_u32 s95, s95, 0
	global_load_dwordx4 v[130:133], v153, s[74:75] offset:256
	global_load_dwordx4 v[176:179], v153, s[82:83] offset:256
	global_load_dwordx4 v[134:137], v153, s[76:77] offset:256
	global_load_dwordx4 v[180:183], v153, s[84:85] offset:256
	global_load_dwordx4 v[138:141], v153, s[78:79] offset:256
	global_load_dwordx4 v[184:187], v153, s[86:87] offset:256
	global_load_dwordx4 v[142:145], v153, s[80:81] offset:256
	global_load_dwordx4 v[188:191], v153, s[92:93] offset:256
	global_load_dwordx4 v[160:163], v153, s[74:75] offset:384
	global_load_dwordx4 v[192:195], v153, s[82:83] offset:384
	global_load_dwordx4 v[164:167], v153, s[76:77] offset:384
	global_load_dwordx4 v[196:199], v153, s[84:85] offset:384
	global_load_dwordx4 v[168:171], v153, s[78:79] offset:384
	global_load_dwordx4 v[200:203], v153, s[86:87] offset:384
	global_load_dwordx4 v[172:175], v153, s[80:81] offset:384
	global_load_dwordx4 v[204:207], v153, s[92:93] offset:384
	s_waitcnt vmcnt(23)
	ds_write_b128 v149, v[34:37] offset:36864
	s_waitcnt vmcnt(22)
	ds_write_b128 v152, v[38:41] offset:36864
	s_waitcnt vmcnt(21)
;     ...
;   for (int kt = 0; kt < nk; ++kt) {
;     __syncthreads();
;     if (kt + 1 < nk) {
;       u16* aw = As0 + ((kt + 1) & 1) * 256 * LD;
;       u16* bw = Bs0 + ((kt + 1) & 1) * 256 * LD;
; #pragma unroll
;       for (int i = 0; i < 4; ++i) { *(u32x4*)(aw + (srow + 64 * i) * LD + skc * 8) = ra[i]; *(u32x4*)(bw + (srow + 64 * i) * LD + skc * 8) = rb[i]; }
;     }
;     if (kt + 2 < nk) {
; #pragma unroll
;       for (int i = 0; i < 4; ++i) { ra[i] = *(const u32x4*)(Ag + (size_t)(64 * i) * K + (kt + 2) * 64); rb[i] = *(const u32x4*)(Bg[i] + (kt + 2) * 64); }
;     }
;     __builtin_amdgcn_sched_barrier(0);
;     const u16* as = As0 + (kt & 1) * 256 * LD + (wr * 128 + l31) * LD + h * 8;
;     const u16* bs = Bs0 + (kt & 1) * 256 * LD + (wc * 64 + l31) * LD + h * 8;
;     if (domma)
; #pragma unroll
;     for (int ks = 0; ks < 4; ++ks) {
;       bf16x8 wf[2], xf[4];
; #pragma unroll
;       for (int ct = 0; ct < 2; ++ct) wf[ct] = *(const bf16x8*)(bs + ct * 32 * LD + ks * 16);
; #pragma unroll
;       for (int tt = 0; tt < 4; ++tt) xf[tt] = *(const bf16x8*)(as + tt * 32 * LD + ks * 16);
; #pragma unroll
;       for (int ct = 0; ct < 2; ++ct)
; #pragma unroll
;         for (int tt = 0; tt < 4; ++tt) acc[ct][tt] = __builtin_amdgcn_mfma_f32_32x32x16_bf16(wf[ct], xf[tt], acc[ct][tt], 0, 0, 0);
;     }
	ds_write_b128 v149, v[42:45] offset:46080
	s_waitcnt vmcnt(20)
	ds_write_b128 v149, v[46:49] offset:55296
	s_waitcnt vmcnt(19)
	ds_write_b128 v152, v[50:53] offset:46080
	s_waitcnt vmcnt(18)
	ds_write_b128 v152, v[54:57] offset:55296
	s_waitcnt vmcnt(17)
	ds_write_b128 v149, v[58:61] offset:64512
	s_waitcnt vmcnt(16)
	ds_write_b128 v152, v[62:65] offset:64512
	ds_read_b128 v[208:211], v148
	ds_read_b128 v[228:231], v147
	ds_read_b128 v[212:215], v148 offset:4608
	ds_read_b128 v[232:235], v147 offset:4608
	ds_read_b128 v[236:239], v147 offset:9216
	ds_read_b128 v[240:243], v147 offset:13824
	s_waitcnt lgkmcnt(4)
	v_mfma_f32_32x32x16_bf16 v[98:113], v[208:211], v[228:231], 0
	ds_read_b128 v[216:219], v148 offset:32
	s_waitcnt lgkmcnt(4)
	v_mfma_f32_32x32x16_bf16 v[114:129], v[212:215], v[228:231], 0
	ds_read_b128 v[244:247], v147 offset:32
	s_waitcnt lgkmcnt(4)
	v_mfma_f32_32x32x16_bf16 v[82:97], v[208:211], v[232:235], 0
	ds_read_b128 v[224:227], v148 offset:4640
	v_mfma_f32_32x32x16_bf16 v[66:81], v[212:215], v[232:235], 0
	ds_read_b128 v[228:231], v147 offset:4640
	s_waitcnt lgkmcnt(5)
	v_mfma_f32_32x32x16_bf16 v[50:65], v[208:211], v[236:239], 0
	ds_read_b128 v[232:235], v147 offset:9248
	v_mfma_f32_32x32x16_bf16 v[34:49], v[212:215], v[236:239], 0
	s_waitcnt lgkmcnt(5)
	v_mfma_f32_32x32x16_bf16 v[18:33], v[208:211], v[240:243], 0
	ds_read_b128 v[236:239], v147 offset:13856
	v_mfma_f32_32x32x16_bf16 v[2:17], v[212:215], v[240:243], 0
	s_waitcnt lgkmcnt(4)
	v_mfma_f32_32x32x16_bf16 v[98:113], v[216:219], v[244:247], v[98:113]
	ds_read_b128 v[208:211], v148 offset:64
	s_waitcnt lgkmcnt(4)
	v_mfma_f32_32x32x16_bf16 v[114:129], v[224:227], v[244:247], v[114:129]
	ds_read_b128 v[240:243], v147 offset:64
	s_waitcnt lgkmcnt(4)
	v_mfma_f32_32x32x16_bf16 v[82:97], v[216:219], v[228:231], v[82:97]
	ds_read_b128 v[212:215], v148 offset:4672
	v_mfma_f32_32x32x16_bf16 v[66:81], v[224:227], v[228:231], v[66:81]
	ds_read_b128 v[244:247], v147 offset:4672
	s_waitcnt lgkmcnt(5)
	v_mfma_f32_32x32x16_bf16 v[50:65], v[216:219], v[232:235], v[50:65]
	ds_read_b128 v[228:231], v147 offset:9280
	v_mfma_f32_32x32x16_bf16 v[34:49], v[224:227], v[232:235], v[34:49]
	s_waitcnt lgkmcnt(5)
	v_mfma_f32_32x32x16_bf16 v[18:33], v[216:219], v[236:239], v[18:33]
	ds_read_b128 v[232:235], v147 offset:13888
	v_mfma_f32_32x32x16_bf16 v[2:17], v[224:227], v[236:239], v[2:17]
	s_waitcnt lgkmcnt(4)
	v_mfma_f32_32x32x16_bf16 v[98:113], v[208:211], v[240:243], v[98:113]
	ds_read_b128 v[216:219], v148 offset:96
	s_waitcnt lgkmcnt(4)
	v_mfma_f32_32x32x16_bf16 v[114:129], v[212:215], v[240:243], v[114:129]
	ds_read_b128 v[236:239], v147 offset:96
	s_waitcnt lgkmcnt(4)
	v_mfma_f32_32x32x16_bf16 v[82:97], v[208:211], v[244:247], v[82:97]
	ds_read_b128 v[224:227], v148 offset:4704
	v_mfma_f32_32x32x16_bf16 v[66:81], v[212:215], v[244:247], v[66:81]
	ds_read_b128 v[240:243], v147 offset:4704
	s_waitcnt lgkmcnt(5)
	v_mfma_f32_32x32x16_bf16 v[50:65], v[208:211], v[228:231], v[50:65]
	ds_read_b128 v[244:247], v147 offset:9312
	v_mfma_f32_32x32x16_bf16 v[34:49], v[212:215], v[228:231], v[34:49]
	s_waitcnt lgkmcnt(5)
	v_mfma_f32_32x32x16_bf16 v[18:33], v[208:211], v[232:235], v[18:33]
	ds_read_b128 v[228:231], v147 offset:13920
	v_mfma_f32_32x32x16_bf16 v[2:17], v[212:215], v[232:235], v[2:17]
	s_waitcnt lgkmcnt(4)
	v_mfma_f32_32x32x16_bf16 v[98:113], v[216:219], v[236:239], v[98:113]
	s_waitcnt lgkmcnt(3)
	v_mfma_f32_32x32x16_bf16 v[114:129], v[224:227], v[236:239], v[114:129]
	s_waitcnt lgkmcnt(2)
	v_mfma_f32_32x32x16_bf16 v[82:97], v[216:219], v[240:243], v[82:97]
	v_mfma_f32_32x32x16_bf16 v[66:81], v[224:227], v[240:243], v[66:81]
	s_waitcnt lgkmcnt(1)
	v_mfma_f32_32x32x16_bf16 v[50:65], v[216:219], v[244:247], v[50:65]
	v_mfma_f32_32x32x16_bf16 v[34:49], v[224:227], v[244:247], v[34:49]
	s_waitcnt lgkmcnt(0)
	v_mfma_f32_32x32x16_bf16 v[18:33], v[216:219], v[228:231], v[18:33]
	v_mfma_f32_32x32x16_bf16 v[2:17], v[224:227], v[228:231], v[2:17]
	s_barrier
	ds_read_b128 v[208:211], v148 offset:36864
	ds_read_b128 v[228:231], v147 offset:36864
	ds_read_b128 v[212:215], v148 offset:41472
	ds_read_b128 v[232:235], v147 offset:41472
	ds_read_b128 v[236:239], v147 offset:46080
	ds_read_b128 v[240:243], v147 offset:50688
	s_waitcnt lgkmcnt(4)
	v_mfma_f32_32x32x16_bf16 v[98:113], v[208:211], v[228:231], v[98:113]
	ds_read_b128 v[216:219], v148 offset:36896
	s_waitcnt lgkmcnt(4)
	v_mfma_f32_32x32x16_bf16 v[114:129], v[212:215], v[228:231], v[114:129]
	ds_read_b128 v[244:247], v147 offset:36896
	s_waitcnt lgkmcnt(4)
	v_mfma_f32_32x32x16_bf16 v[82:97], v[208:211], v[232:235], v[82:97]
	ds_read_b128 v[224:227], v148 offset:41504
	v_mfma_f32_32x32x16_bf16 v[66:81], v[212:215], v[232:235], v[66:81]
	ds_read_b128 v[228:231], v147 offset:41504
	s_waitcnt vmcnt(15)
	ds_write_b128 v149, v[130:133]
	s_waitcnt lgkmcnt(6)
	v_mfma_f32_32x32x16_bf16 v[50:65], v[208:211], v[236:239], v[50:65]
	ds_read_b128 v[232:235], v147 offset:46112
	v_mfma_f32_32x32x16_bf16 v[34:49], v[212:215], v[236:239], v[34:49]
	global_load_dwordx4 v[130:133], v153, s[74:75] offset:512
	s_waitcnt lgkmcnt(6)
	v_mfma_f32_32x32x16_bf16 v[18:33], v[208:211], v[240:243], v[18:33]
	ds_read_b128 v[236:239], v147 offset:50720
	s_waitcnt vmcnt(15)
	ds_write_b128 v152, v[176:179]
	v_mfma_f32_32x32x16_bf16 v[2:17], v[212:215], v[240:243], v[2:17]
	s_waitcnt lgkmcnt(6)
	v_mfma_f32_32x32x16_bf16 v[98:113], v[216:219], v[244:247], v[98:113]
	ds_read_b128 v[208:211], v148 offset:36928
	global_load_dwordx4 v[176:179], v153, s[82:83] offset:512
	s_waitcnt lgkmcnt(6)
	v_mfma_f32_32x32x16_bf16 v[114:129], v[224:227], v[244:247], v[114:129]
	ds_read_b128 v[240:243], v147 offset:36928
	s_waitcnt vmcnt(15)
;     ...
;   for (int kt = 0; kt < nk; ++kt) {
;     __syncthreads();
;     if (kt + 1 < nk) {
;       u16* aw = As0 + ((kt + 1) & 1) * 256 * LD;
;       u16* bw = Bs0 + ((kt + 1) & 1) * 256 * LD;
; #pragma unroll
;       for (int i = 0; i < 4; ++i) { *(u32x4*)(aw + (srow + 64 * i) * LD + skc * 8) = ra[i]; *(u32x4*)(bw + (srow + 64 * i) * LD + skc * 8) = rb[i]; }
;     }
;     if (kt + 2 < nk) {
; #pragma unroll
;       for (int i = 0; i < 4; ++i) { ra[i] = *(const u32x4*)(Ag + (size_t)(64 * i) * K + (kt + 2) * 64); rb[i] = *(const u32x4*)(Bg[i] + (kt + 2) * 64); }
;     }
;     __builtin_amdgcn_sched_barrier(0);
;     const u16* as = As0 + (kt & 1) * 256 * LD + (wr * 128 + l31) * LD + h * 8;
;     const u16* bs = Bs0 + (kt & 1) * 256 * LD + (wc * 64 + l31) * LD + h * 8;
;     if (domma)
; #pragma unroll
;     for (int ks = 0; ks < 4; ++ks) {
;       bf16x8 wf[2], xf[4];
; #pragma unroll
;       for (int ct = 0; ct < 2; ++ct) wf[ct] = *(const bf16x8*)(bs + ct * 32 * LD + ks * 16);
; #pragma unroll
;       for (int tt = 0; tt < 4; ++tt) xf[tt] = *(const bf16x8*)(as + tt * 32 * LD + ks * 16);
; #pragma unroll
;       for (int ct = 0; ct < 2; ++ct)
; #pragma unroll
;         for (int tt = 0; tt < 4; ++tt) acc[ct][tt] = __builtin_amdgcn_mfma_f32_32x32x16_bf16(wf[ct], xf[tt], acc[ct][tt], 0, 0, 0);
;     }
;     __builtin_amdgcn_sched_barrier(0);
;   }
	ds_write_b128 v149, v[134:137] offset:9216
	s_waitcnt lgkmcnt(7)
	v_mfma_f32_32x32x16_bf16 v[82:97], v[216:219], v[228:231], v[82:97]
	ds_read_b128 v[212:215], v148 offset:41536
	v_mfma_f32_32x32x16_bf16 v[66:81], v[224:227], v[228:231], v[66:81]
	ds_read_b128 v[244:247], v147 offset:41536
	global_load_dwordx4 v[134:137], v153, s[76:77] offset:512
	s_waitcnt lgkmcnt(7)
	v_mfma_f32_32x32x16_bf16 v[50:65], v[216:219], v[232:235], v[50:65]
	ds_read_b128 v[228:231], v147 offset:46144
	s_waitcnt vmcnt(15)
	ds_write_b128 v152, v[180:183] offset:9216
	v_mfma_f32_32x32x16_bf16 v[34:49], v[224:227], v[232:235], v[34:49]
	s_waitcnt lgkmcnt(8)
	v_mfma_f32_32x32x16_bf16 v[18:33], v[216:219], v[236:239], v[18:33]
	ds_read_b128 v[232:235], v147 offset:50752
	global_load_dwordx4 v[180:183], v153, s[84:85] offset:512
	v_mfma_f32_32x32x16_bf16 v[2:17], v[224:227], v[236:239], v[2:17]
	s_waitcnt vmcnt(15)
	ds_write_b128 v149, v[138:141] offset:18432
	s_waitcnt lgkmcnt(7)
	v_mfma_f32_32x32x16_bf16 v[98:113], v[208:211], v[240:243], v[98:113]
	ds_read_b128 v[216:219], v148 offset:36960
	s_waitcnt lgkmcnt(6)
	v_mfma_f32_32x32x16_bf16 v[114:129], v[212:215], v[240:243], v[114:129]
	ds_read_b128 v[236:239], v147 offset:36960
	global_load_dwordx4 v[138:141], v153, s[78:79] offset:512
	s_waitcnt lgkmcnt(6)
	v_mfma_f32_32x32x16_bf16 v[82:97], v[208:211], v[244:247], v[82:97]
	ds_read_b128 v[224:227], v148 offset:41568
	s_waitcnt vmcnt(15)
	ds_write_b128 v152, v[184:187] offset:18432
	v_mfma_f32_32x32x16_bf16 v[66:81], v[212:215], v[244:247], v[66:81]
	ds_read_b128 v[240:243], v147 offset:41568
	s_waitcnt lgkmcnt(8)
	v_mfma_f32_32x32x16_bf16 v[50:65], v[208:211], v[228:231], v[50:65]
	ds_read_b128 v[244:247], v147 offset:46176
	global_load_dwordx4 v[184:187], v153, s[86:87] offset:512
	v_mfma_f32_32x32x16_bf16 v[34:49], v[212:215], v[228:231], v[34:49]
	s_waitcnt vmcnt(15)
	ds_write_b128 v149, v[142:145] offset:27648
	s_waitcnt lgkmcnt(8)
	v_mfma_f32_32x32x16_bf16 v[18:33], v[208:211], v[232:235], v[18:33]
	ds_read_b128 v[228:231], v147 offset:50784
	v_mfma_f32_32x32x16_bf16 v[2:17], v[212:215], v[232:235], v[2:17]
	global_load_dwordx4 v[142:145], v153, s[80:81] offset:512
	s_waitcnt lgkmcnt(6)
	v_mfma_f32_32x32x16_bf16 v[98:113], v[216:219], v[236:239], v[98:113]
	s_waitcnt vmcnt(15)
	ds_write_b128 v152, v[188:191] offset:27648
	s_waitcnt lgkmcnt(6)
	v_mfma_f32_32x32x16_bf16 v[114:129], v[224:227], v[236:239], v[114:129]
	s_waitcnt lgkmcnt(4)
	v_mfma_f32_32x32x16_bf16 v[82:97], v[216:219], v[240:243], v[82:97]
	global_load_dwordx4 v[188:191], v153, s[92:93] offset:512
	v_mfma_f32_32x32x16_bf16 v[66:81], v[224:227], v[240:243], v[66:81]
	s_waitcnt lgkmcnt(3)
	v_mfma_f32_32x32x16_bf16 v[50:65], v[216:219], v[244:247], v[50:65]
	v_mfma_f32_32x32x16_bf16 v[34:49], v[224:227], v[244:247], v[34:49]
	s_waitcnt lgkmcnt(1)
	v_mfma_f32_32x32x16_bf16 v[18:33], v[216:219], v[228:231], v[18:33]
	v_mfma_f32_32x32x16_bf16 v[2:17], v[224:227], v[228:231], v[2:17]
	s_waitcnt lgkmcnt(0)
	s_barrier
	ds_read_b128 v[208:211], v148
	ds_read_b128 v[228:231], v147
	ds_read_b128 v[212:215], v148 offset:4608
	ds_read_b128 v[232:235], v147 offset:4608
	ds_read_b128 v[236:239], v147 offset:9216
	ds_read_b128 v[240:243], v147 offset:13824
	s_waitcnt lgkmcnt(4)
	v_mfma_f32_32x32x16_bf16 v[98:113], v[208:211], v[228:231], v[98:113]
	ds_read_b128 v[216:219], v148 offset:32
	s_waitcnt lgkmcnt(4)
	v_mfma_f32_32x32x16_bf16 v[114:129], v[212:215], v[228:231], v[114:129]
	ds_read_b128 v[244:247], v147 offset:32
	s_waitcnt lgkmcnt(4)
	v_mfma_f32_32x32x16_bf16 v[82:97], v[208:211], v[232:235], v[82:97]
	ds_read_b128 v[224:227], v148 offset:4640
	v_mfma_f32_32x32x16_bf16 v[66:81], v[212:215], v[232:235], v[66:81]
	ds_read_b128 v[228:231], v147 offset:4640
	s_waitcnt vmcnt(15)
	ds_write_b128 v149, v[160:163] offset:36864
	s_waitcnt lgkmcnt(6)
	v_mfma_f32_32x32x16_bf16 v[50:65], v[208:211], v[236:239], v[50:65]
	ds_read_b128 v[232:235], v147 offset:9248
	v_mfma_f32_32x32x16_bf16 v[34:49], v[212:215], v[236:239], v[34:49]
	global_load_dwordx4 v[160:163], v153, s[74:75] offset:640
	s_waitcnt lgkmcnt(6)
	v_mfma_f32_32x32x16_bf16 v[18:33], v[208:211], v[240:243], v[18:33]
	ds_read_b128 v[236:239], v147 offset:13856
	s_waitcnt vmcnt(15)
	ds_write_b128 v152, v[192:195] offset:36864
	v_mfma_f32_32x32x16_bf16 v[2:17], v[212:215], v[240:243], v[2:17]
	s_waitcnt lgkmcnt(6)
	v_mfma_f32_32x32x16_bf16 v[98:113], v[216:219], v[244:247], v[98:113]
	ds_read_b128 v[208:211], v148 offset:64
	global_load_dwordx4 v[192:195], v153, s[82:83] offset:640
	s_waitcnt lgkmcnt(6)
	v_mfma_f32_32x32x16_bf16 v[114:129], v[224:227], v[244:247], v[114:129]
	ds_read_b128 v[240:243], v147 offset:64
	s_waitcnt vmcnt(15)
	ds_write_b128 v149, v[164:167] offset:46080
	s_waitcnt lgkmcnt(7)
	v_mfma_f32_32x32x16_bf16 v[82:97], v[216:219], v[228:231], v[82:97]
	ds_read_b128 v[212:215], v148 offset:4672
	v_mfma_f32_32x32x16_bf16 v[66:81], v[224:227], v[228:231], v[66:81]
	ds_read_b128 v[244:247], v147 offset:4672
	global_load_dwordx4 v[164:167], v153, s[76:77] offset:640
	s_waitcnt lgkmcnt(7)
	v_mfma_f32_32x32x16_bf16 v[50:65], v[216:219], v[232:235], v[50:65]
	ds_read_b128 v[228:231], v147 offset:9280
	s_waitcnt vmcnt(15)
	ds_write_b128 v152, v[196:199] offset:46080
	v_mfma_f32_32x32x16_bf16 v[34:49], v[224:227], v[232:235], v[34:49]
	s_waitcnt lgkmcnt(8)
	v_mfma_f32_32x32x16_bf16 v[18:33], v[216:219], v[236:239], v[18:33]
	ds_read_b128 v[232:235], v147 offset:13888
	global_load_dwordx4 v[196:199], v153, s[84:85] offset:640
	v_mfma_f32_32x32x16_bf16 v[2:17], v[224:227], v[236:239], v[2:17]
	s_waitcnt vmcnt(15)
;     ...
;   for (int kt = 0; kt < nk; ++kt) {
;     __syncthreads();
;     if (kt + 1 < nk) {
;       u16* aw = As0 + ((kt + 1) & 1) * 256 * LD;
;       u16* bw = Bs0 + ((kt + 1) & 1) * 256 * LD;
; #pragma unroll
;       for (int i = 0; i < 4; ++i) { *(u32x4*)(aw + (srow + 64 * i) * LD + skc * 8) = ra[i]; *(u32x4*)(bw + (srow + 64 * i) * LD + skc * 8) = rb[i]; }
;     }
;     if (kt + 2 < nk) {
; #pragma unroll
;       for (int i = 0; i < 4; ++i) { ra[i] = *(const u32x4*)(Ag + (size_t)(64 * i) * K + (kt + 2) * 64); rb[i] = *(const u32x4*)(Bg[i] + (kt + 2) * 64); }
;     }
;     __builtin_amdgcn_sched_barrier(0);
;     const u16* as = As0 + (kt & 1) * 256 * LD + (wr * 128 + l31) * LD + h * 8;
;     const u16* bs = Bs0 + (kt & 1) * 256 * LD + (wc * 64 + l31) * LD + h * 8;
;     if (domma)
; #pragma unroll
;     for (int ks = 0; ks < 4; ++ks) {
;       bf16x8 wf[2], xf[4];
; #pragma unroll
;       for (int ct = 0; ct < 2; ++ct) wf[ct] = *(const bf16x8*)(bs + ct * 32 * LD + ks * 16);
; #pragma unroll
;       for (int tt = 0; tt < 4; ++tt) xf[tt] = *(const bf16x8*)(as + tt * 32 * LD + ks * 16);
; #pragma unroll
;       for (int ct = 0; ct < 2; ++ct)
; #pragma unroll
;         for (int tt = 0; tt < 4; ++tt) acc[ct][tt] = __builtin_amdgcn_mfma_f32_32x32x16_bf16(wf[ct], xf[tt], acc[ct][tt], 0, 0, 0);
;     }
;     __builtin_amdgcn_sched_barrier(0);
;   }
	ds_write_b128 v149, v[168:171] offset:55296
	s_waitcnt lgkmcnt(7)
	v_mfma_f32_32x32x16_bf16 v[98:113], v[208:211], v[240:243], v[98:113]
	ds_read_b128 v[216:219], v148 offset:96
	s_waitcnt lgkmcnt(6)
	v_mfma_f32_32x32x16_bf16 v[114:129], v[212:215], v[240:243], v[114:129]
	ds_read_b128 v[236:239], v147 offset:96
	global_load_dwordx4 v[168:171], v153, s[78:79] offset:640
	s_waitcnt lgkmcnt(6)
	v_mfma_f32_32x32x16_bf16 v[82:97], v[208:211], v[244:247], v[82:97]
	ds_read_b128 v[224:227], v148 offset:4704
	s_waitcnt vmcnt(15)
	ds_write_b128 v152, v[200:203] offset:55296
	v_mfma_f32_32x32x16_bf16 v[66:81], v[212:215], v[244:247], v[66:81]
	ds_read_b128 v[240:243], v147 offset:4704
	s_waitcnt lgkmcnt(8)
	v_mfma_f32_32x32x16_bf16 v[50:65], v[208:211], v[228:231], v[50:65]
	ds_read_b128 v[244:247], v147 offset:9312
	global_load_dwordx4 v[200:203], v153, s[86:87] offset:640
	v_mfma_f32_32x32x16_bf16 v[34:49], v[212:215], v[228:231], v[34:49]
	s_waitcnt vmcnt(15)
	ds_write_b128 v149, v[172:175] offset:64512
	s_waitcnt lgkmcnt(8)
	v_mfma_f32_32x32x16_bf16 v[18:33], v[208:211], v[232:235], v[18:33]
	ds_read_b128 v[228:231], v147 offset:13920
	v_mfma_f32_32x32x16_bf16 v[2:17], v[212:215], v[232:235], v[2:17]
	global_load_dwordx4 v[172:175], v153, s[80:81] offset:640
	s_waitcnt lgkmcnt(6)
	v_mfma_f32_32x32x16_bf16 v[98:113], v[216:219], v[236:239], v[98:113]
	s_waitcnt vmcnt(15)
	ds_write_b128 v152, v[204:207] offset:64512
	s_waitcnt lgkmcnt(6)
	v_mfma_f32_32x32x16_bf16 v[114:129], v[224:227], v[236:239], v[114:129]
	s_waitcnt lgkmcnt(4)
	v_mfma_f32_32x32x16_bf16 v[82:97], v[216:219], v[240:243], v[82:97]
	global_load_dwordx4 v[204:207], v153, s[92:93] offset:640
	v_mfma_f32_32x32x16_bf16 v[66:81], v[224:227], v[240:243], v[66:81]
	s_waitcnt lgkmcnt(3)
	v_mfma_f32_32x32x16_bf16 v[50:65], v[216:219], v[244:247], v[50:65]
	v_mfma_f32_32x32x16_bf16 v[34:49], v[224:227], v[244:247], v[34:49]
	s_waitcnt lgkmcnt(1)
	v_mfma_f32_32x32x16_bf16 v[18:33], v[216:219], v[228:231], v[18:33]
	v_mfma_f32_32x32x16_bf16 v[2:17], v[224:227], v[228:231], v[2:17]
	s_waitcnt lgkmcnt(0)
	s_barrier
	ds_read_b128 v[208:211], v148 offset:36864
	ds_read_b128 v[228:231], v147 offset:36864
	ds_read_b128 v[212:215], v148 offset:41472
	ds_read_b128 v[232:235], v147 offset:41472
	ds_read_b128 v[236:239], v147 offset:46080
	ds_read_b128 v[240:243], v147 offset:50688
	s_waitcnt lgkmcnt(4)
	v_mfma_f32_32x32x16_bf16 v[98:113], v[208:211], v[228:231], v[98:113]
	ds_read_b128 v[216:219], v148 offset:36896
	s_waitcnt lgkmcnt(4)
	v_mfma_f32_32x32x16_bf16 v[114:129], v[212:215], v[228:231], v[114:129]
	ds_read_b128 v[244:247], v147 offset:36896
	s_waitcnt lgkmcnt(4)
	v_mfma_f32_32x32x16_bf16 v[82:97], v[208:211], v[232:235], v[82:97]
	ds_read_b128 v[224:227], v148 offset:41504
	v_mfma_f32_32x32x16_bf16 v[66:81], v[212:215], v[232:235], v[66:81]
	ds_read_b128 v[228:231], v147 offset:41504
	s_waitcnt vmcnt(15)
	ds_write_b128 v149, v[130:133]
	s_waitcnt lgkmcnt(6)
	v_mfma_f32_32x32x16_bf16 v[50:65], v[208:211], v[236:239], v[50:65]
	ds_read_b128 v[232:235], v147 offset:46112
	v_mfma_f32_32x32x16_bf16 v[34:49], v[212:215], v[236:239], v[34:49]
	global_load_dwordx4 v[130:133], v153, s[74:75] offset:768
	s_waitcnt lgkmcnt(6)
	v_mfma_f32_32x32x16_bf16 v[18:33], v[208:211], v[240:243], v[18:33]
	ds_read_b128 v[236:239], v147 offset:50720
	s_waitcnt vmcnt(15)
	ds_write_b128 v152, v[176:179]
	v_mfma_f32_32x32x16_bf16 v[2:17], v[212:215], v[240:243], v[2:17]
	s_waitcnt lgkmcnt(6)
	v_mfma_f32_32x32x16_bf16 v[98:113], v[216:219], v[244:247], v[98:113]
	ds_read_b128 v[208:211], v148 offset:36928
	global_load_dwordx4 v[176:179], v153, s[82:83] offset:768
	s_waitcnt lgkmcnt(6)
	v_mfma_f32_32x32x16_bf16 v[114:129], v[224:227], v[244:247], v[114:129]
	ds_read_b128 v[240:243], v147 offset:36928
	s_waitcnt vmcnt(15)
	ds_write_b128 v149, v[134:137] offset:9216
	s_waitcnt lgkmcnt(7)
	v_mfma_f32_32x32x16_bf16 v[82:97], v[216:219], v[228:231], v[82:97]
	ds_read_b128 v[212:215], v148 offset:41536
	v_mfma_f32_32x32x16_bf16 v[66:81], v[224:227], v[228:231], v[66:81]
	ds_read_b128 v[244:247], v147 offset:41536
	global_load_dwordx4 v[134:137], v153, s[76:77] offset:768
	s_waitcnt lgkmcnt(7)
	v_mfma_f32_32x32x16_bf16 v[50:65], v[216:219], v[232:235], v[50:65]
	ds_read_b128 v[228:231], v147 offset:46144
	s_waitcnt vmcnt(15)
	ds_write_b128 v152, v[180:183] offset:9216
	v_mfma_f32_32x32x16_bf16 v[34:49], v[224:227], v[232:235], v[34:49]
	s_waitcnt lgkmcnt(8)
	v_mfma_f32_32x32x16_bf16 v[18:33], v[216:219], v[236:239], v[18:33]
	ds_read_b128 v[232:235], v147 offset:50752
	global_load_dwordx4 v[180:183], v153, s[84:85] offset:768
	v_mfma_f32_32x32x16_bf16 v[2:17], v[224:227], v[236:239], v[2:17]
	s_waitcnt vmcnt(15)
	ds_write_b128 v149, v[138:141] offset:18432
	s_waitcnt lgkmcnt(7)
	v_mfma_f32_32x32x16_bf16 v[98:113], v[208:211], v[240:243], v[98:113]
	ds_read_b128 v[216:219], v148 offset:36960
	s_waitcnt lgkmcnt(6)
	v_mfma_f32_32x32x16_bf16 v[114:129], v[212:215], v[240:243], v[114:129]
	ds_read_b128 v[236:239], v147 offset:36960
	global_load_dwordx4 v[138:141], v153, s[78:79] offset:768
	s_waitcnt lgkmcnt(6)
	v_mfma_f32_32x32x16_bf16 v[82:97], v[208:211], v[244:247], v[82:97]
	ds_read_b128 v[224:227], v148 offset:41568
	s_waitcnt vmcnt(15)
	ds_write_b128 v152, v[184:187] offset:18432
	v_mfma_f32_32x32x16_bf16 v[66:81], v[212:215], v[244:247], v[66:81]
	ds_read_b128 v[240:243], v147 offset:41568
	s_waitcnt lgkmcnt(8)
	v_mfma_f32_32x32x16_bf16 v[50:65], v[208:211], v[228:231], v[50:65]
	ds_read_b128 v[244:247], v147 offset:46176
	global_load_dwordx4 v[184:187], v153, s[86:87] offset:768
	v_mfma_f32_32x32x16_bf16 v[34:49], v[212:215], v[228:231], v[34:49]
	s_waitcnt vmcnt(15)
	ds_write_b128 v149, v[142:145] offset:27648
	s_waitcnt lgkmcnt(8)
	v_mfma_f32_32x32x16_bf16 v[18:33], v[208:211], v[232:235], v[18:33]
	ds_read_b128 v[228:231], v147 offset:50784
	v_mfma_f32_32x32x16_bf16 v[2:17], v[212:215], v[232:235], v[2:17]
	global_load_dwordx4 v[142:145], v153, s[80:81] offset:768
	s_waitcnt lgkmcnt(6)
	v_mfma_f32_32x32x16_bf16 v[98:113], v[216:219], v[236:239], v[98:113]
	s_waitcnt vmcnt(15)
	ds_write_b128 v152, v[188:191] offset:27648
	s_waitcnt lgkmcnt(6)
	v_mfma_f32_32x32x16_bf16 v[114:129], v[224:227], v[236:239], v[114:129]
	s_waitcnt lgkmcnt(4)
	v_mfma_f32_32x32x16_bf16 v[82:97], v[216:219], v[240:243], v[82:97]
	global_load_dwordx4 v[188:191], v153, s[92:93] offset:768
	v_mfma_f32_32x32x16_bf16 v[66:81], v[224:227], v[240:243], v[66:81]
	s_waitcnt lgkmcnt(3)
	v_mfma_f32_32x32x16_bf16 v[50:65], v[216:219], v[244:247], v[50:65]
	v_mfma_f32_32x32x16_bf16 v[34:49], v[224:227], v[244:247], v[34:49]
	s_waitcnt lgkmcnt(1)
	v_mfma_f32_32x32x16_bf16 v[18:33], v[216:219], v[228:231], v[18:33]
	v_mfma_f32_32x32x16_bf16 v[2:17], v[224:227], v[228:231], v[2:17]
	s_waitcnt lgkmcnt(0)
	s_barrier
;     ...
;   for (int kt = 0; kt < nk; ++kt) {
;     __syncthreads();
;     if (kt + 1 < nk) {
;       u16* aw = As0 + ((kt + 1) & 1) * 256 * LD;
;       u16* bw = Bs0 + ((kt + 1) & 1) * 256 * LD;
; #pragma unroll
;       for (int i = 0; i < 4; ++i) { *(u32x4*)(aw + (srow + 64 * i) * LD + skc * 8) = ra[i]; *(u32x4*)(bw + (srow + 64 * i) * LD + skc * 8) = rb[i]; }
;     }
;     if (kt + 2 < nk) {
; #pragma unroll
;       for (int i = 0; i < 4; ++i) { ra[i] = *(const u32x4*)(Ag + (size_t)(64 * i) * K + (kt + 2) * 64); rb[i] = *(const u32x4*)(Bg[i] + (kt + 2) * 64); }
;     }
;     __builtin_amdgcn_sched_barrier(0);
;     const u16* as = As0 + (kt & 1) * 256 * LD + (wr * 128 + l31) * LD + h * 8;
;     const u16* bs = Bs0 + (kt & 1) * 256 * LD + (wc * 64 + l31) * LD + h * 8;
;     if (domma)
; #pragma unroll
;     for (int ks = 0; ks < 4; ++ks) {
;       bf16x8 wf[2], xf[4];
; #pragma unroll
;       for (int ct = 0; ct < 2; ++ct) wf[ct] = *(const bf16x8*)(bs + ct * 32 * LD + ks * 16);
; #pragma unroll
;       for (int tt = 0; tt < 4; ++tt) xf[tt] = *(const bf16x8*)(as + tt * 32 * LD + ks * 16);
; #pragma unroll
;       for (int ct = 0; ct < 2; ++ct)
; #pragma unroll
;         for (int tt = 0; tt < 4; ++tt) acc[ct][tt] = __builtin_amdgcn_mfma_f32_32x32x16_bf16(wf[ct], xf[tt], acc[ct][tt], 0, 0, 0);
;     }
;     __builtin_amdgcn_sched_barrier(0);
;   }
	ds_read_b128 v[208:211], v148
	ds_read_b128 v[228:231], v147
	ds_read_b128 v[212:215], v148 offset:4608
	ds_read_b128 v[232:235], v147 offset:4608
	ds_read_b128 v[236:239], v147 offset:9216
	ds_read_b128 v[240:243], v147 offset:13824
	s_waitcnt lgkmcnt(4)
	v_mfma_f32_32x32x16_bf16 v[98:113], v[208:211], v[228:231], v[98:113]
	ds_read_b128 v[216:219], v148 offset:32
	s_waitcnt lgkmcnt(4)
	v_mfma_f32_32x32x16_bf16 v[114:129], v[212:215], v[228:231], v[114:129]
	ds_read_b128 v[244:247], v147 offset:32
	s_waitcnt lgkmcnt(4)
	v_mfma_f32_32x32x16_bf16 v[82:97], v[208:211], v[232:235], v[82:97]
	ds_read_b128 v[224:227], v148 offset:4640
	v_mfma_f32_32x32x16_bf16 v[66:81], v[212:215], v[232:235], v[66:81]
	ds_read_b128 v[228:231], v147 offset:4640
	s_waitcnt vmcnt(15)
	ds_write_b128 v149, v[160:163] offset:36864
	s_waitcnt lgkmcnt(6)
	v_mfma_f32_32x32x16_bf16 v[50:65], v[208:211], v[236:239], v[50:65]
	ds_read_b128 v[232:235], v147 offset:9248
	v_mfma_f32_32x32x16_bf16 v[34:49], v[212:215], v[236:239], v[34:49]
	global_load_dwordx4 v[160:163], v153, s[74:75] offset:896
	s_waitcnt lgkmcnt(6)
	v_mfma_f32_32x32x16_bf16 v[18:33], v[208:211], v[240:243], v[18:33]
	ds_read_b128 v[236:239], v147 offset:13856
	s_waitcnt vmcnt(15)
	ds_write_b128 v152, v[192:195] offset:36864
	v_mfma_f32_32x32x16_bf16 v[2:17], v[212:215], v[240:243], v[2:17]
	s_waitcnt lgkmcnt(6)
	v_mfma_f32_32x32x16_bf16 v[98:113], v[216:219], v[244:247], v[98:113]
	ds_read_b128 v[208:211], v148 offset:64
	global_load_dwordx4 v[192:195], v153, s[82:83] offset:896
	s_waitcnt lgkmcnt(6)
	v_mfma_f32_32x32x16_bf16 v[114:129], v[224:227], v[244:247], v[114:129]
	ds_read_b128 v[240:243], v147 offset:64
	s_waitcnt vmcnt(15)
	ds_write_b128 v149, v[164:167] offset:46080
	s_waitcnt lgkmcnt(7)
	v_mfma_f32_32x32x16_bf16 v[82:97], v[216:219], v[228:231], v[82:97]
	ds_read_b128 v[212:215], v148 offset:4672
	v_mfma_f32_32x32x16_bf16 v[66:81], v[224:227], v[228:231], v[66:81]
	ds_read_b128 v[244:247], v147 offset:4672
	global_load_dwordx4 v[164:167], v153, s[76:77] offset:896
	s_waitcnt lgkmcnt(7)
	v_mfma_f32_32x32x16_bf16 v[50:65], v[216:219], v[232:235], v[50:65]
	ds_read_b128 v[228:231], v147 offset:9280
	s_waitcnt vmcnt(15)
	ds_write_b128 v152, v[196:199] offset:46080
	v_mfma_f32_32x32x16_bf16 v[34:49], v[224:227], v[232:235], v[34:49]
	s_waitcnt lgkmcnt(8)
	v_mfma_f32_32x32x16_bf16 v[18:33], v[216:219], v[236:239], v[18:33]
	ds_read_b128 v[232:235], v147 offset:13888
	global_load_dwordx4 v[196:199], v153, s[84:85] offset:896
	v_mfma_f32_32x32x16_bf16 v[2:17], v[224:227], v[236:239], v[2:17]
	s_waitcnt vmcnt(15)
	ds_write_b128 v149, v[168:171] offset:55296
	s_waitcnt lgkmcnt(7)
	v_mfma_f32_32x32x16_bf16 v[98:113], v[208:211], v[240:243], v[98:113]
	ds_read_b128 v[216:219], v148 offset:96
	s_waitcnt lgkmcnt(6)
	v_mfma_f32_32x32x16_bf16 v[114:129], v[212:215], v[240:243], v[114:129]
	ds_read_b128 v[236:239], v147 offset:96
	global_load_dwordx4 v[168:171], v153, s[78:79] offset:896
	s_waitcnt lgkmcnt(6)
	v_mfma_f32_32x32x16_bf16 v[82:97], v[208:211], v[244:247], v[82:97]
	ds_read_b128 v[224:227], v148 offset:4704
	s_waitcnt vmcnt(15)
	ds_write_b128 v152, v[200:203] offset:55296
	v_mfma_f32_32x32x16_bf16 v[66:81], v[212:215], v[244:247], v[66:81]
	ds_read_b128 v[240:243], v147 offset:4704
	s_waitcnt lgkmcnt(8)
	v_mfma_f32_32x32x16_bf16 v[50:65], v[208:211], v[228:231], v[50:65]
	ds_read_b128 v[244:247], v147 offset:9312
	global_load_dwordx4 v[200:203], v153, s[86:87] offset:896
	v_mfma_f32_32x32x16_bf16 v[34:49], v[212:215], v[228:231], v[34:49]
	s_waitcnt vmcnt(15)
	ds_write_b128 v149, v[172:175] offset:64512
	s_waitcnt lgkmcnt(8)
	v_mfma_f32_32x32x16_bf16 v[18:33], v[208:211], v[232:235], v[18:33]
	ds_read_b128 v[228:231], v147 offset:13920
	v_mfma_f32_32x32x16_bf16 v[2:17], v[212:215], v[232:235], v[2:17]
	global_load_dwordx4 v[172:175], v153, s[80:81] offset:896
	s_waitcnt lgkmcnt(6)
	v_mfma_f32_32x32x16_bf16 v[98:113], v[216:219], v[236:239], v[98:113]
	s_waitcnt vmcnt(15)
	ds_write_b128 v152, v[204:207] offset:64512
	s_waitcnt lgkmcnt(6)
	v_mfma_f32_32x32x16_bf16 v[114:129], v[224:227], v[236:239], v[114:129]
	s_waitcnt lgkmcnt(4)
	v_mfma_f32_32x32x16_bf16 v[82:97], v[216:219], v[240:243], v[82:97]
	global_load_dwordx4 v[204:207], v153, s[92:93] offset:896
	v_mfma_f32_32x32x16_bf16 v[66:81], v[224:227], v[240:243], v[66:81]
	s_waitcnt lgkmcnt(3)
	v_mfma_f32_32x32x16_bf16 v[50:65], v[216:219], v[244:247], v[50:65]
	v_mfma_f32_32x32x16_bf16 v[34:49], v[224:227], v[244:247], v[34:49]
	s_waitcnt lgkmcnt(1)
	v_mfma_f32_32x32x16_bf16 v[18:33], v[216:219], v[228:231], v[18:33]
	v_mfma_f32_32x32x16_bf16 v[2:17], v[224:227], v[228:231], v[2:17]
	s_waitcnt lgkmcnt(0)
	s_barrier
;     ...
;   for (int kt = 0; kt < nk; ++kt) {
;     __syncthreads();
;     if (kt + 1 < nk) {
;       u16* aw = As0 + ((kt + 1) & 1) * 256 * LD;
;       u16* bw = Bs0 + ((kt + 1) & 1) * 256 * LD;
; #pragma unroll
;       for (int i = 0; i < 4; ++i) { *(u32x4*)(aw + (srow + 64 * i) * LD + skc * 8) = ra[i]; *(u32x4*)(bw + (srow + 64 * i) * LD + skc * 8) = rb[i]; }
;     }
;     if (kt + 2 < nk) {
; #pragma unroll
;       for (int i = 0; i < 4; ++i) { ra[i] = *(const u32x4*)(Ag + (size_t)(64 * i) * K + (kt + 2) * 64); rb[i] = *(const u32x4*)(Bg[i] + (kt + 2) * 64); }
;     }
;     __builtin_amdgcn_sched_barrier(0);
;     const u16* as = As0 + (kt & 1) * 256 * LD + (wr * 128 + l31) * LD + h * 8;
;     const u16* bs = Bs0 + (kt & 1) * 256 * LD + (wc * 64 + l31) * LD + h * 8;
;     if (domma)
; #pragma unroll
;     for (int ks = 0; ks < 4; ++ks) {
;       bf16x8 wf[2], xf[4];
; #pragma unroll
;       for (int ct = 0; ct < 2; ++ct) wf[ct] = *(const bf16x8*)(bs + ct * 32 * LD + ks * 16);
; #pragma unroll
;       for (int tt = 0; tt < 4; ++tt) xf[tt] = *(const bf16x8*)(as + tt * 32 * LD + ks * 16);
; #pragma unroll
;       for (int ct = 0; ct < 2; ++ct)
; #pragma unroll
;         for (int tt = 0; tt < 4; ++tt) acc[ct][tt] = __builtin_amdgcn_mfma_f32_32x32x16_bf16(wf[ct], xf[tt], acc[ct][tt], 0, 0, 0);
;     }
;     __builtin_amdgcn_sched_barrier(0);
;   }
	ds_read_b128 v[208:211], v148 offset:36864
	ds_read_b128 v[228:231], v147 offset:36864
	ds_read_b128 v[212:215], v148 offset:41472
	ds_read_b128 v[232:235], v147 offset:41472
	ds_read_b128 v[236:239], v147 offset:46080
	ds_read_b128 v[240:243], v147 offset:50688
	s_waitcnt lgkmcnt(4)
	v_mfma_f32_32x32x16_bf16 v[98:113], v[208:211], v[228:231], v[98:113]
	ds_read_b128 v[216:219], v148 offset:36896
	s_waitcnt lgkmcnt(4)
	v_mfma_f32_32x32x16_bf16 v[114:129], v[212:215], v[228:231], v[114:129]
	ds_read_b128 v[244:247], v147 offset:36896
	s_waitcnt lgkmcnt(4)
	v_mfma_f32_32x32x16_bf16 v[82:97], v[208:211], v[232:235], v[82:97]
	ds_read_b128 v[224:227], v148 offset:41504
	v_mfma_f32_32x32x16_bf16 v[66:81], v[212:215], v[232:235], v[66:81]
	ds_read_b128 v[228:231], v147 offset:41504
	s_waitcnt vmcnt(15)
	ds_write_b128 v149, v[130:133]
	s_waitcnt lgkmcnt(6)
	v_mfma_f32_32x32x16_bf16 v[50:65], v[208:211], v[236:239], v[50:65]
	ds_read_b128 v[232:235], v147 offset:46112
	v_mfma_f32_32x32x16_bf16 v[34:49], v[212:215], v[236:239], v[34:49]
	global_load_dwordx4 v[130:133], v153, s[74:75] offset:1024
	s_waitcnt lgkmcnt(6)
	v_mfma_f32_32x32x16_bf16 v[18:33], v[208:211], v[240:243], v[18:33]
	ds_read_b128 v[236:239], v147 offset:50720
	s_waitcnt vmcnt(15)
	ds_write_b128 v152, v[176:179]
	v_mfma_f32_32x32x16_bf16 v[2:17], v[212:215], v[240:243], v[2:17]
	s_waitcnt lgkmcnt(6)
	v_mfma_f32_32x32x16_bf16 v[98:113], v[216:219], v[244:247], v[98:113]
	ds_read_b128 v[208:211], v148 offset:36928
	global_load_dwordx4 v[176:179], v153, s[82:83] offset:1024
	s_waitcnt lgkmcnt(6)
	v_mfma_f32_32x32x16_bf16 v[114:129], v[224:227], v[244:247], v[114:129]
	ds_read_b128 v[240:243], v147 offset:36928
	s_waitcnt vmcnt(15)
	ds_write_b128 v149, v[134:137] offset:9216
	s_waitcnt lgkmcnt(7)
	v_mfma_f32_32x32x16_bf16 v[82:97], v[216:219], v[228:231], v[82:97]
	ds_read_b128 v[212:215], v148 offset:41536
	v_mfma_f32_32x32x16_bf16 v[66:81], v[224:227], v[228:231], v[66:81]
	ds_read_b128 v[244:247], v147 offset:41536
	global_load_dwordx4 v[134:137], v153, s[76:77] offset:1024
	s_waitcnt lgkmcnt(7)
	v_mfma_f32_32x32x16_bf16 v[50:65], v[216:219], v[232:235], v[50:65]
	ds_read_b128 v[228:231], v147 offset:46144
	s_waitcnt vmcnt(15)
	ds_write_b128 v152, v[180:183] offset:9216
	v_mfma_f32_32x32x16_bf16 v[34:49], v[224:227], v[232:235], v[34:49]
	s_waitcnt lgkmcnt(8)
	v_mfma_f32_32x32x16_bf16 v[18:33], v[216:219], v[236:239], v[18:33]
	ds_read_b128 v[232:235], v147 offset:50752
	global_load_dwordx4 v[180:183], v153, s[84:85] offset:1024
	v_mfma_f32_32x32x16_bf16 v[2:17], v[224:227], v[236:239], v[2:17]
	s_waitcnt vmcnt(15)
	ds_write_b128 v149, v[138:141] offset:18432
	s_waitcnt lgkmcnt(7)
	v_mfma_f32_32x32x16_bf16 v[98:113], v[208:211], v[240:243], v[98:113]
	ds_read_b128 v[216:219], v148 offset:36960
	s_waitcnt lgkmcnt(6)
	v_mfma_f32_32x32x16_bf16 v[114:129], v[212:215], v[240:243], v[114:129]
	ds_read_b128 v[236:239], v147 offset:36960
	global_load_dwordx4 v[138:141], v153, s[78:79] offset:1024
	s_waitcnt lgkmcnt(6)
	v_mfma_f32_32x32x16_bf16 v[82:97], v[208:211], v[244:247], v[82:97]
	ds_read_b128 v[224:227], v148 offset:41568
	s_waitcnt vmcnt(15)
	ds_write_b128 v152, v[184:187] offset:18432
	v_mfma_f32_32x32x16_bf16 v[66:81], v[212:215], v[244:247], v[66:81]
	ds_read_b128 v[240:243], v147 offset:41568
	s_waitcnt lgkmcnt(8)
	v_mfma_f32_32x32x16_bf16 v[50:65], v[208:211], v[228:231], v[50:65]
	ds_read_b128 v[244:247], v147 offset:46176
	global_load_dwordx4 v[184:187], v153, s[86:87] offset:1024
	v_mfma_f32_32x32x16_bf16 v[34:49], v[212:215], v[228:231], v[34:49]
	s_waitcnt vmcnt(15)
	ds_write_b128 v149, v[142:145] offset:27648
	s_waitcnt lgkmcnt(8)
	v_mfma_f32_32x32x16_bf16 v[18:33], v[208:211], v[232:235], v[18:33]
	ds_read_b128 v[228:231], v147 offset:50784
	v_mfma_f32_32x32x16_bf16 v[2:17], v[212:215], v[232:235], v[2:17]
	global_load_dwordx4 v[142:145], v153, s[80:81] offset:1024
	s_waitcnt lgkmcnt(6)
	v_mfma_f32_32x32x16_bf16 v[98:113], v[216:219], v[236:239], v[98:113]
	s_waitcnt vmcnt(15)
	ds_write_b128 v152, v[188:191] offset:27648
	s_waitcnt lgkmcnt(6)
	v_mfma_f32_32x32x16_bf16 v[114:129], v[224:227], v[236:239], v[114:129]
	s_waitcnt lgkmcnt(4)
	v_mfma_f32_32x32x16_bf16 v[82:97], v[216:219], v[240:243], v[82:97]
	global_load_dwordx4 v[188:191], v153, s[92:93] offset:1024
	v_mfma_f32_32x32x16_bf16 v[66:81], v[224:227], v[240:243], v[66:81]
	s_waitcnt lgkmcnt(3)
	v_mfma_f32_32x32x16_bf16 v[50:65], v[216:219], v[244:247], v[50:65]
	v_mfma_f32_32x32x16_bf16 v[34:49], v[224:227], v[244:247], v[34:49]
	s_waitcnt lgkmcnt(1)
	v_mfma_f32_32x32x16_bf16 v[18:33], v[216:219], v[228:231], v[18:33]
	v_mfma_f32_32x32x16_bf16 v[2:17], v[224:227], v[228:231], v[2:17]
	s_waitcnt lgkmcnt(0)
	s_barrier
;     ...
;   for (int kt = 0; kt < nk; ++kt) {
;     __syncthreads();
;     if (kt + 1 < nk) {
;       u16* aw = As0 + ((kt + 1) & 1) * 256 * LD;
;       u16* bw = Bs0 + ((kt + 1) & 1) * 256 * LD;
; #pragma unroll
;       for (int i = 0; i < 4; ++i) { *(u32x4*)(aw + (srow + 64 * i) * LD + skc * 8) = ra[i]; *(u32x4*)(bw + (srow + 64 * i) * LD + skc * 8) = rb[i]; }
;     }
;     if (kt + 2 < nk) {
; #pragma unroll
;       for (int i = 0; i < 4; ++i) { ra[i] = *(const u32x4*)(Ag + (size_t)(64 * i) * K + (kt + 2) * 64); rb[i] = *(const u32x4*)(Bg[i] + (kt + 2) * 64); }
;     }
;     __builtin_amdgcn_sched_barrier(0);
;     const u16* as = As0 + (kt & 1) * 256 * LD + (wr * 128 + l31) * LD + h * 8;
;     const u16* bs = Bs0 + (kt & 1) * 256 * LD + (wc * 64 + l31) * LD + h * 8;
;     if (domma)
; #pragma unroll
;     for (int ks = 0; ks < 4; ++ks) {
;       bf16x8 wf[2], xf[4];
; #pragma unroll
;       for (int ct = 0; ct < 2; ++ct) wf[ct] = *(const bf16x8*)(bs + ct * 32 * LD + ks * 16);
; #pragma unroll
;       for (int tt = 0; tt < 4; ++tt) xf[tt] = *(const bf16x8*)(as + tt * 32 * LD + ks * 16);
; #pragma unroll
;       for (int ct = 0; ct < 2; ++ct)
; #pragma unroll
;         for (int tt = 0; tt < 4; ++tt) acc[ct][tt] = __builtin_amdgcn_mfma_f32_32x32x16_bf16(wf[ct], xf[tt], acc[ct][tt], 0, 0, 0);
;     }
;     __builtin_amdgcn_sched_barrier(0);
;   }
; __device__ void phase_gemm2(const Params& p, char* lds, int bid, int nb, bool fused) {
;     ...
;         const float* xr = p.x + (size_t)tok * DM + n0 + wc * 64;
;         float ss = 0.f;
; #pragma unroll
;         for (int ct = 0; ct < 2; ++ct)
; #pragma unroll
;           for (int rq = 0; rq < 4; ++rq) {
;             const f32x4 xv = *(const f32x4*)(xr + ct * 32 + 8 * rq + 4 * h);
	ds_read_b128 v[208:211], v148
	ds_read_b128 v[228:231], v147
	ds_read_b128 v[212:215], v148 offset:4608
	ds_read_b128 v[232:235], v147 offset:4608
	ds_read_b128 v[236:239], v147 offset:9216
	ds_read_b128 v[240:243], v147 offset:13824
	s_waitcnt lgkmcnt(4)
	v_mfma_f32_32x32x16_bf16 v[98:113], v[208:211], v[228:231], v[98:113]
	ds_read_b128 v[216:219], v148 offset:32
	s_waitcnt lgkmcnt(4)
	v_mfma_f32_32x32x16_bf16 v[114:129], v[212:215], v[228:231], v[114:129]
	ds_read_b128 v[244:247], v147 offset:32
	s_waitcnt lgkmcnt(4)
	v_mfma_f32_32x32x16_bf16 v[82:97], v[208:211], v[232:235], v[82:97]
	ds_read_b128 v[224:227], v148 offset:4640
	v_mfma_f32_32x32x16_bf16 v[66:81], v[212:215], v[232:235], v[66:81]
	ds_read_b128 v[228:231], v147 offset:4640
	s_waitcnt vmcnt(15)
	ds_write_b128 v149, v[160:163] offset:36864
	s_waitcnt lgkmcnt(6)
	v_mfma_f32_32x32x16_bf16 v[50:65], v[208:211], v[236:239], v[50:65]
	ds_read_b128 v[232:235], v147 offset:9248
	v_mfma_f32_32x32x16_bf16 v[34:49], v[212:215], v[236:239], v[34:49]
	global_load_dwordx4 v[160:163], v153, s[74:75] offset:1152
	s_waitcnt lgkmcnt(6)
	v_mfma_f32_32x32x16_bf16 v[18:33], v[208:211], v[240:243], v[18:33]
	ds_read_b128 v[236:239], v147 offset:13856
	s_waitcnt vmcnt(15)
	ds_write_b128 v152, v[192:195] offset:36864
	v_mfma_f32_32x32x16_bf16 v[2:17], v[212:215], v[240:243], v[2:17]
	s_waitcnt lgkmcnt(6)
	v_mfma_f32_32x32x16_bf16 v[98:113], v[216:219], v[244:247], v[98:113]
	ds_read_b128 v[208:211], v148 offset:64
	global_load_dwordx4 v[192:195], v153, s[82:83] offset:1152
	s_waitcnt lgkmcnt(6)
	v_mfma_f32_32x32x16_bf16 v[114:129], v[224:227], v[244:247], v[114:129]
	ds_read_b128 v[240:243], v147 offset:64
	s_waitcnt vmcnt(15)
	ds_write_b128 v149, v[164:167] offset:46080
	s_waitcnt lgkmcnt(7)
	v_mfma_f32_32x32x16_bf16 v[82:97], v[216:219], v[228:231], v[82:97]
	ds_read_b128 v[212:215], v148 offset:4672
	v_mfma_f32_32x32x16_bf16 v[66:81], v[224:227], v[228:231], v[66:81]
	ds_read_b128 v[244:247], v147 offset:4672
	global_load_dwordx4 v[164:167], v153, s[76:77] offset:1152
	s_waitcnt lgkmcnt(7)
	v_mfma_f32_32x32x16_bf16 v[50:65], v[216:219], v[232:235], v[50:65]
	ds_read_b128 v[228:231], v147 offset:9280
	s_waitcnt vmcnt(15)
	ds_write_b128 v152, v[196:199] offset:46080
	global_load_dword v155, v154, s[94:95]
	v_mfma_f32_32x32x16_bf16 v[34:49], v[224:227], v[232:235], v[34:49]
	s_waitcnt lgkmcnt(8)
	v_mfma_f32_32x32x16_bf16 v[18:33], v[216:219], v[236:239], v[18:33]
	ds_read_b128 v[232:235], v147 offset:13888
	global_load_dwordx4 v[196:199], v153, s[84:85] offset:1152
	v_mfma_f32_32x32x16_bf16 v[2:17], v[224:227], v[236:239], v[2:17]
	s_waitcnt vmcnt(16)
	ds_write_b128 v149, v[168:171] offset:55296
	s_waitcnt lgkmcnt(7)
	v_mfma_f32_32x32x16_bf16 v[98:113], v[208:211], v[240:243], v[98:113]
	ds_read_b128 v[216:219], v148 offset:96
	s_waitcnt lgkmcnt(6)
	v_mfma_f32_32x32x16_bf16 v[114:129], v[212:215], v[240:243], v[114:129]
	ds_read_b128 v[236:239], v147 offset:96
	global_load_dwordx4 v[168:171], v153, s[78:79] offset:1152
	s_waitcnt lgkmcnt(6)
	v_mfma_f32_32x32x16_bf16 v[82:97], v[208:211], v[244:247], v[82:97]
	ds_read_b128 v[224:227], v148 offset:4704
	s_waitcnt vmcnt(16)
	ds_write_b128 v152, v[200:203] offset:55296
	v_mfma_f32_32x32x16_bf16 v[66:81], v[212:215], v[244:247], v[66:81]
	ds_read_b128 v[240:243], v147 offset:4704
	s_waitcnt lgkmcnt(8)
	v_mfma_f32_32x32x16_bf16 v[50:65], v[208:211], v[228:231], v[50:65]
	ds_read_b128 v[244:247], v147 offset:9312
	global_load_dwordx4 v[200:203], v153, s[86:87] offset:1152
	v_mfma_f32_32x32x16_bf16 v[34:49], v[212:215], v[228:231], v[34:49]
	s_waitcnt vmcnt(16)
	ds_write_b128 v149, v[172:175] offset:64512
	s_waitcnt lgkmcnt(8)
	v_mfma_f32_32x32x16_bf16 v[18:33], v[208:211], v[232:235], v[18:33]
	ds_read_b128 v[228:231], v147 offset:13920
	v_mfma_f32_32x32x16_bf16 v[2:17], v[212:215], v[232:235], v[2:17]
	global_load_dwordx4 v[172:175], v153, s[80:81] offset:1152
	s_waitcnt lgkmcnt(6)
	v_mfma_f32_32x32x16_bf16 v[98:113], v[216:219], v[236:239], v[98:113]
	s_waitcnt vmcnt(16)
	ds_write_b128 v152, v[204:207] offset:64512
	s_waitcnt lgkmcnt(6)
	v_mfma_f32_32x32x16_bf16 v[114:129], v[224:227], v[236:239], v[114:129]
	s_waitcnt lgkmcnt(4)
	v_mfma_f32_32x32x16_bf16 v[82:97], v[216:219], v[240:243], v[82:97]
	global_load_dwordx4 v[204:207], v153, s[92:93] offset:1152
	v_mfma_f32_32x32x16_bf16 v[66:81], v[224:227], v[240:243], v[66:81]
	s_waitcnt lgkmcnt(3)
	v_mfma_f32_32x32x16_bf16 v[50:65], v[216:219], v[244:247], v[50:65]
	v_mfma_f32_32x32x16_bf16 v[34:49], v[224:227], v[244:247], v[34:49]
	s_waitcnt lgkmcnt(1)
	v_mfma_f32_32x32x16_bf16 v[18:33], v[216:219], v[228:231], v[18:33]
	v_mfma_f32_32x32x16_bf16 v[2:17], v[224:227], v[228:231], v[2:17]
	s_waitcnt lgkmcnt(0)
	s_barrier
;     ...
;   for (int kt = 0; kt < nk; ++kt) {
;     __syncthreads();
;     if (kt + 1 < nk) {
;       u16* aw = As0 + ((kt + 1) & 1) * 256 * LD;
;       u16* bw = Bs0 + ((kt + 1) & 1) * 256 * LD;
; #pragma unroll
;       for (int i = 0; i < 4; ++i) { *(u32x4*)(aw + (srow + 64 * i) * LD + skc * 8) = ra[i]; *(u32x4*)(bw + (srow + 64 * i) * LD + skc * 8) = rb[i]; }
;     }
;     if (kt + 2 < nk) {
; #pragma unroll
;       for (int i = 0; i < 4; ++i) { ra[i] = *(const u32x4*)(Ag + (size_t)(64 * i) * K + (kt + 2) * 64); rb[i] = *(const u32x4*)(Bg[i] + (kt + 2) * 64); }
;     }
;     __builtin_amdgcn_sched_barrier(0);
;     const u16* as = As0 + (kt & 1) * 256 * LD + (wr * 128 + l31) * LD + h * 8;
;     const u16* bs = Bs0 + (kt & 1) * 256 * LD + (wc * 64 + l31) * LD + h * 8;
;     if (domma)
; #pragma unroll
;     for (int ks = 0; ks < 4; ++ks) {
;       bf16x8 wf[2], xf[4];
; #pragma unroll
;       for (int ct = 0; ct < 2; ++ct) wf[ct] = *(const bf16x8*)(bs + ct * 32 * LD + ks * 16);
; #pragma unroll
;       for (int tt = 0; tt < 4; ++tt) xf[tt] = *(const bf16x8*)(as + tt * 32 * LD + ks * 16);
; #pragma unroll
;       for (int ct = 0; ct < 2; ++ct)
; #pragma unroll
;         for (int tt = 0; tt < 4; ++tt) acc[ct][tt] = __builtin_amdgcn_mfma_f32_32x32x16_bf16(wf[ct], xf[tt], acc[ct][tt], 0, 0, 0);
;     }
;     __builtin_amdgcn_sched_barrier(0);
;   }
; __device__ void phase_gemm2(const Params& p, char* lds, int bid, int nb, bool fused) {
;     ...
;         const float* xr = p.x + (size_t)tok * DM + n0 + wc * 64;
;         float ss = 0.f;
; #pragma unroll
;         for (int ct = 0; ct < 2; ++ct)
; #pragma unroll
;           for (int rq = 0; rq < 4; ++rq) {
;             const f32x4 xv = *(const f32x4*)(xr + ct * 32 + 8 * rq + 4 * h);
	ds_read_b128 v[208:211], v148 offset:36864
	ds_read_b128 v[228:231], v147 offset:36864
	ds_read_b128 v[212:215], v148 offset:41472
	ds_read_b128 v[232:235], v147 offset:41472
	ds_read_b128 v[236:239], v147 offset:46080
	ds_read_b128 v[240:243], v147 offset:50688
	s_waitcnt lgkmcnt(4)
	v_mfma_f32_32x32x16_bf16 v[98:113], v[208:211], v[228:231], v[98:113]
	ds_read_b128 v[216:219], v148 offset:36896
	s_waitcnt lgkmcnt(4)
	v_mfma_f32_32x32x16_bf16 v[114:129], v[212:215], v[228:231], v[114:129]
	ds_read_b128 v[244:247], v147 offset:36896
	s_waitcnt lgkmcnt(4)
	v_mfma_f32_32x32x16_bf16 v[82:97], v[208:211], v[232:235], v[82:97]
	ds_read_b128 v[224:227], v148 offset:41504
	v_mfma_f32_32x32x16_bf16 v[66:81], v[212:215], v[232:235], v[66:81]
	ds_read_b128 v[228:231], v147 offset:41504
	s_waitcnt vmcnt(16)
	ds_write_b128 v149, v[130:133]
	s_waitcnt lgkmcnt(6)
	v_mfma_f32_32x32x16_bf16 v[50:65], v[208:211], v[236:239], v[50:65]
	ds_read_b128 v[232:235], v147 offset:46112
	v_mfma_f32_32x32x16_bf16 v[34:49], v[212:215], v[236:239], v[34:49]
	global_load_dwordx4 v[130:133], v153, s[74:75] offset:1280
	s_waitcnt lgkmcnt(6)
	v_mfma_f32_32x32x16_bf16 v[18:33], v[208:211], v[240:243], v[18:33]
	ds_read_b128 v[236:239], v147 offset:50720
	s_waitcnt vmcnt(16)
	ds_write_b128 v152, v[176:179]
	v_mfma_f32_32x32x16_bf16 v[2:17], v[212:215], v[240:243], v[2:17]
	s_waitcnt lgkmcnt(6)
	v_mfma_f32_32x32x16_bf16 v[98:113], v[216:219], v[244:247], v[98:113]
	ds_read_b128 v[208:211], v148 offset:36928
	global_load_dwordx4 v[176:179], v153, s[82:83] offset:1280
	s_waitcnt lgkmcnt(6)
	v_mfma_f32_32x32x16_bf16 v[114:129], v[224:227], v[244:247], v[114:129]
	ds_read_b128 v[240:243], v147 offset:36928
	s_waitcnt vmcnt(16)
	ds_write_b128 v149, v[134:137] offset:9216
	s_waitcnt lgkmcnt(7)
	v_mfma_f32_32x32x16_bf16 v[82:97], v[216:219], v[228:231], v[82:97]
	ds_read_b128 v[212:215], v148 offset:41536
	v_mfma_f32_32x32x16_bf16 v[66:81], v[224:227], v[228:231], v[66:81]
	ds_read_b128 v[244:247], v147 offset:41536
	global_load_dwordx4 v[134:137], v153, s[76:77] offset:1280
	s_waitcnt lgkmcnt(7)
	v_mfma_f32_32x32x16_bf16 v[50:65], v[216:219], v[232:235], v[50:65]
	ds_read_b128 v[228:231], v147 offset:46144
	s_waitcnt vmcnt(16)
	ds_write_b128 v152, v[180:183] offset:9216
	global_load_dword v155, v154, s[94:95] offset:128
	v_mfma_f32_32x32x16_bf16 v[34:49], v[224:227], v[232:235], v[34:49]
	s_waitcnt lgkmcnt(8)
	v_mfma_f32_32x32x16_bf16 v[18:33], v[216:219], v[236:239], v[18:33]
	ds_read_b128 v[232:235], v147 offset:50752
	global_load_dwordx4 v[180:183], v153, s[84:85] offset:1280
	v_mfma_f32_32x32x16_bf16 v[2:17], v[224:227], v[236:239], v[2:17]
	s_waitcnt vmcnt(17)
	ds_write_b128 v149, v[138:141] offset:18432
	s_waitcnt lgkmcnt(7)
	v_mfma_f32_32x32x16_bf16 v[98:113], v[208:211], v[240:243], v[98:113]
	ds_read_b128 v[216:219], v148 offset:36960
	s_waitcnt lgkmcnt(6)
	v_mfma_f32_32x32x16_bf16 v[114:129], v[212:215], v[240:243], v[114:129]
	ds_read_b128 v[236:239], v147 offset:36960
	global_load_dwordx4 v[138:141], v153, s[78:79] offset:1280
	s_waitcnt lgkmcnt(6)
	v_mfma_f32_32x32x16_bf16 v[82:97], v[208:211], v[244:247], v[82:97]
	ds_read_b128 v[224:227], v148 offset:41568
	s_waitcnt vmcnt(17)
	ds_write_b128 v152, v[184:187] offset:18432
	v_mfma_f32_32x32x16_bf16 v[66:81], v[212:215], v[244:247], v[66:81]
	ds_read_b128 v[240:243], v147 offset:41568
	s_waitcnt lgkmcnt(8)
	v_mfma_f32_32x32x16_bf16 v[50:65], v[208:211], v[228:231], v[50:65]
	ds_read_b128 v[244:247], v147 offset:46176
	global_load_dwordx4 v[184:187], v153, s[86:87] offset:1280
	v_mfma_f32_32x32x16_bf16 v[34:49], v[212:215], v[228:231], v[34:49]
	s_waitcnt vmcnt(17)
	ds_write_b128 v149, v[142:145] offset:27648
	s_waitcnt lgkmcnt(8)
	v_mfma_f32_32x32x16_bf16 v[18:33], v[208:211], v[232:235], v[18:33]
	ds_read_b128 v[228:231], v147 offset:50784
	v_mfma_f32_32x32x16_bf16 v[2:17], v[212:215], v[232:235], v[2:17]
	global_load_dwordx4 v[142:145], v153, s[80:81] offset:1280
	s_waitcnt lgkmcnt(6)
	v_mfma_f32_32x32x16_bf16 v[98:113], v[216:219], v[236:239], v[98:113]
	s_waitcnt vmcnt(17)
	ds_write_b128 v152, v[188:191] offset:27648
	s_waitcnt lgkmcnt(6)
	v_mfma_f32_32x32x16_bf16 v[114:129], v[224:227], v[236:239], v[114:129]
	s_waitcnt lgkmcnt(4)
	v_mfma_f32_32x32x16_bf16 v[82:97], v[216:219], v[240:243], v[82:97]
	global_load_dwordx4 v[188:191], v153, s[92:93] offset:1280
	v_mfma_f32_32x32x16_bf16 v[66:81], v[224:227], v[240:243], v[66:81]
	s_waitcnt lgkmcnt(3)
	v_mfma_f32_32x32x16_bf16 v[50:65], v[216:219], v[244:247], v[50:65]
	v_mfma_f32_32x32x16_bf16 v[34:49], v[224:227], v[244:247], v[34:49]
	s_waitcnt lgkmcnt(1)
	v_mfma_f32_32x32x16_bf16 v[18:33], v[216:219], v[228:231], v[18:33]
	v_mfma_f32_32x32x16_bf16 v[2:17], v[224:227], v[228:231], v[2:17]
	s_waitcnt lgkmcnt(0)
	s_barrier
;     ...
;   for (int kt = 0; kt < nk; ++kt) {
;     __syncthreads();
;     if (kt + 1 < nk) {
;       u16* aw = As0 + ((kt + 1) & 1) * 256 * LD;
;       u16* bw = Bs0 + ((kt + 1) & 1) * 256 * LD;
; #pragma unroll
;       for (int i = 0; i < 4; ++i) { *(u32x4*)(aw + (srow + 64 * i) * LD + skc * 8) = ra[i]; *(u32x4*)(bw + (srow + 64 * i) * LD + skc * 8) = rb[i]; }
;     }
;     if (kt + 2 < nk) {
; #pragma unroll
;       for (int i = 0; i < 4; ++i) { ra[i] = *(const u32x4*)(Ag + (size_t)(64 * i) * K + (kt + 2) * 64); rb[i] = *(const u32x4*)(Bg[i] + (kt + 2) * 64); }
;     }
;     __builtin_amdgcn_sched_barrier(0);
;     const u16* as = As0 + (kt & 1) * 256 * LD + (wr * 128 + l31) * LD + h * 8;
;     const u16* bs = Bs0 + (kt & 1) * 256 * LD + (wc * 64 + l31) * LD + h * 8;
;     if (domma)
; #pragma unroll
;     for (int ks = 0; ks < 4; ++ks) {
;       bf16x8 wf[2], xf[4];
; #pragma unroll
;       for (int ct = 0; ct < 2; ++ct) wf[ct] = *(const bf16x8*)(bs + ct * 32 * LD + ks * 16);
; #pragma unroll
;       for (int tt = 0; tt < 4; ++tt) xf[tt] = *(const bf16x8*)(as + tt * 32 * LD + ks * 16);
; #pragma unroll
;       for (int ct = 0; ct < 2; ++ct)
; #pragma unroll
;         for (int tt = 0; tt < 4; ++tt) acc[ct][tt] = __builtin_amdgcn_mfma_f32_32x32x16_bf16(wf[ct], xf[tt], acc[ct][tt], 0, 0, 0);
;     }
;     __builtin_amdgcn_sched_barrier(0);
;   }
; __device__ void phase_gemm2(const Params& p, char* lds, int bid, int nb, bool fused) {
;     ...
;         const float* xr = p.x + (size_t)tok * DM + n0 + wc * 64;
;         float ss = 0.f;
; #pragma unroll
;         for (int ct = 0; ct < 2; ++ct)
; #pragma unroll
;           for (int rq = 0; rq < 4; ++rq) {
;             const f32x4 xv = *(const f32x4*)(xr + ct * 32 + 8 * rq + 4 * h);
	ds_read_b128 v[208:211], v148
	ds_read_b128 v[228:231], v147
	ds_read_b128 v[212:215], v148 offset:4608
	ds_read_b128 v[232:235], v147 offset:4608
	ds_read_b128 v[236:239], v147 offset:9216
	ds_read_b128 v[240:243], v147 offset:13824
	s_waitcnt lgkmcnt(4)
	v_mfma_f32_32x32x16_bf16 v[98:113], v[208:211], v[228:231], v[98:113]
	ds_read_b128 v[216:219], v148 offset:32
	s_waitcnt lgkmcnt(4)
	v_mfma_f32_32x32x16_bf16 v[114:129], v[212:215], v[228:231], v[114:129]
	ds_read_b128 v[244:247], v147 offset:32
	s_waitcnt lgkmcnt(4)
	v_mfma_f32_32x32x16_bf16 v[82:97], v[208:211], v[232:235], v[82:97]
	ds_read_b128 v[224:227], v148 offset:4640
	v_mfma_f32_32x32x16_bf16 v[66:81], v[212:215], v[232:235], v[66:81]
	ds_read_b128 v[228:231], v147 offset:4640
	s_waitcnt vmcnt(17)
	ds_write_b128 v149, v[160:163] offset:36864
	s_waitcnt lgkmcnt(6)
	v_mfma_f32_32x32x16_bf16 v[50:65], v[208:211], v[236:239], v[50:65]
	ds_read_b128 v[232:235], v147 offset:9248
	v_mfma_f32_32x32x16_bf16 v[34:49], v[212:215], v[236:239], v[34:49]
	global_load_dwordx4 v[160:163], v153, s[74:75] offset:1408
	s_waitcnt lgkmcnt(6)
	v_mfma_f32_32x32x16_bf16 v[18:33], v[208:211], v[240:243], v[18:33]
	ds_read_b128 v[236:239], v147 offset:13856
	s_waitcnt vmcnt(17)
	ds_write_b128 v152, v[192:195] offset:36864
	v_mfma_f32_32x32x16_bf16 v[2:17], v[212:215], v[240:243], v[2:17]
	s_waitcnt lgkmcnt(6)
	v_mfma_f32_32x32x16_bf16 v[98:113], v[216:219], v[244:247], v[98:113]
	ds_read_b128 v[208:211], v148 offset:64
	global_load_dwordx4 v[192:195], v153, s[82:83] offset:1408
	s_waitcnt lgkmcnt(6)
	v_mfma_f32_32x32x16_bf16 v[114:129], v[224:227], v[244:247], v[114:129]
	ds_read_b128 v[240:243], v147 offset:64
	s_waitcnt vmcnt(17)
	ds_write_b128 v149, v[164:167] offset:46080
	s_waitcnt lgkmcnt(7)
	v_mfma_f32_32x32x16_bf16 v[82:97], v[216:219], v[228:231], v[82:97]
	ds_read_b128 v[212:215], v148 offset:4672
	v_mfma_f32_32x32x16_bf16 v[66:81], v[224:227], v[228:231], v[66:81]
	ds_read_b128 v[244:247], v147 offset:4672
	global_load_dwordx4 v[164:167], v153, s[76:77] offset:1408
	s_waitcnt lgkmcnt(7)
	v_mfma_f32_32x32x16_bf16 v[50:65], v[216:219], v[232:235], v[50:65]
	ds_read_b128 v[228:231], v147 offset:9280
	s_waitcnt vmcnt(16)
	ds_write_b128 v152, v[196:199] offset:46080
	global_load_dword v155, v154, s[94:95] offset:256
	v_mfma_f32_32x32x16_bf16 v[34:49], v[224:227], v[232:235], v[34:49]
	s_waitcnt lgkmcnt(8)
	v_mfma_f32_32x32x16_bf16 v[18:33], v[216:219], v[236:239], v[18:33]
	ds_read_b128 v[232:235], v147 offset:13888
	global_load_dwordx4 v[196:199], v153, s[84:85] offset:1408
	v_mfma_f32_32x32x16_bf16 v[2:17], v[224:227], v[236:239], v[2:17]
	s_waitcnt vmcnt(17)
	ds_write_b128 v149, v[168:171] offset:55296
	s_waitcnt lgkmcnt(7)
	v_mfma_f32_32x32x16_bf16 v[98:113], v[208:211], v[240:243], v[98:113]
	ds_read_b128 v[216:219], v148 offset:96
	s_waitcnt lgkmcnt(6)
	v_mfma_f32_32x32x16_bf16 v[114:129], v[212:215], v[240:243], v[114:129]
	ds_read_b128 v[236:239], v147 offset:96
	global_load_dwordx4 v[168:171], v153, s[78:79] offset:1408
	s_waitcnt lgkmcnt(6)
	v_mfma_f32_32x32x16_bf16 v[82:97], v[208:211], v[244:247], v[82:97]
	ds_read_b128 v[224:227], v148 offset:4704
	s_waitcnt vmcnt(17)
	ds_write_b128 v152, v[200:203] offset:55296
	v_mfma_f32_32x32x16_bf16 v[66:81], v[212:215], v[244:247], v[66:81]
	ds_read_b128 v[240:243], v147 offset:4704
	s_waitcnt lgkmcnt(8)
	v_mfma_f32_32x32x16_bf16 v[50:65], v[208:211], v[228:231], v[50:65]
	ds_read_b128 v[244:247], v147 offset:9312
	global_load_dwordx4 v[200:203], v153, s[86:87] offset:1408
	v_mfma_f32_32x32x16_bf16 v[34:49], v[212:215], v[228:231], v[34:49]
	s_waitcnt vmcnt(17)
	ds_write_b128 v149, v[172:175] offset:64512
	s_waitcnt lgkmcnt(8)
	v_mfma_f32_32x32x16_bf16 v[18:33], v[208:211], v[232:235], v[18:33]
	ds_read_b128 v[228:231], v147 offset:13920
	v_mfma_f32_32x32x16_bf16 v[2:17], v[212:215], v[232:235], v[2:17]
	global_load_dwordx4 v[172:175], v153, s[80:81] offset:1408
	s_waitcnt lgkmcnt(6)
	v_mfma_f32_32x32x16_bf16 v[98:113], v[216:219], v[236:239], v[98:113]
	s_waitcnt vmcnt(17)
	ds_write_b128 v152, v[204:207] offset:64512
	s_waitcnt lgkmcnt(6)
	v_mfma_f32_32x32x16_bf16 v[114:129], v[224:227], v[236:239], v[114:129]
	s_waitcnt lgkmcnt(4)
	v_mfma_f32_32x32x16_bf16 v[82:97], v[216:219], v[240:243], v[82:97]
	global_load_dwordx4 v[204:207], v153, s[92:93] offset:1408
	v_mfma_f32_32x32x16_bf16 v[66:81], v[224:227], v[240:243], v[66:81]
	s_waitcnt lgkmcnt(3)
	v_mfma_f32_32x32x16_bf16 v[50:65], v[216:219], v[244:247], v[50:65]
	v_mfma_f32_32x32x16_bf16 v[34:49], v[224:227], v[244:247], v[34:49]
	s_waitcnt lgkmcnt(1)
	v_mfma_f32_32x32x16_bf16 v[18:33], v[216:219], v[228:231], v[18:33]
	v_mfma_f32_32x32x16_bf16 v[2:17], v[224:227], v[228:231], v[2:17]
	s_waitcnt lgkmcnt(0)
	s_barrier
;     ...
;   for (int kt = 0; kt < nk; ++kt) {
;     __syncthreads();
;     if (kt + 1 < nk) {
;       u16* aw = As0 + ((kt + 1) & 1) * 256 * LD;
;       u16* bw = Bs0 + ((kt + 1) & 1) * 256 * LD;
; #pragma unroll
;       for (int i = 0; i < 4; ++i) { *(u32x4*)(aw + (srow + 64 * i) * LD + skc * 8) = ra[i]; *(u32x4*)(bw + (srow + 64 * i) * LD + skc * 8) = rb[i]; }
;     }
;     if (kt + 2 < nk) {
; #pragma unroll
;       for (int i = 0; i < 4; ++i) { ra[i] = *(const u32x4*)(Ag + (size_t)(64 * i) * K + (kt + 2) * 64); rb[i] = *(const u32x4*)(Bg[i] + (kt + 2) * 64); }
;     }
;     __builtin_amdgcn_sched_barrier(0);
;     const u16* as = As0 + (kt & 1) * 256 * LD + (wr * 128 + l31) * LD + h * 8;
;     const u16* bs = Bs0 + (kt & 1) * 256 * LD + (wc * 64 + l31) * LD + h * 8;
;     if (domma)
; #pragma unroll
;     for (int ks = 0; ks < 4; ++ks) {
;       bf16x8 wf[2], xf[4];
; #pragma unroll
;       for (int ct = 0; ct < 2; ++ct) wf[ct] = *(const bf16x8*)(bs + ct * 32 * LD + ks * 16);
; #pragma unroll
;       for (int tt = 0; tt < 4; ++tt) xf[tt] = *(const bf16x8*)(as + tt * 32 * LD + ks * 16);
; #pragma unroll
;       for (int ct = 0; ct < 2; ++ct)
; #pragma unroll
;         for (int tt = 0; tt < 4; ++tt) acc[ct][tt] = __builtin_amdgcn_mfma_f32_32x32x16_bf16(wf[ct], xf[tt], acc[ct][tt], 0, 0, 0);
;     }
;     __builtin_amdgcn_sched_barrier(0);
;   }
	ds_read_b128 v[208:211], v148 offset:36864
	ds_read_b128 v[228:231], v147 offset:36864
	ds_read_b128 v[212:215], v148 offset:41472
	ds_read_b128 v[232:235], v147 offset:41472
	ds_read_b128 v[236:239], v147 offset:46080
	ds_read_b128 v[240:243], v147 offset:50688
	s_waitcnt lgkmcnt(4)
	v_mfma_f32_32x32x16_bf16 v[98:113], v[208:211], v[228:231], v[98:113]
	ds_read_b128 v[216:219], v148 offset:36896
	s_waitcnt lgkmcnt(4)
	v_mfma_f32_32x32x16_bf16 v[114:129], v[212:215], v[228:231], v[114:129]
	ds_read_b128 v[244:247], v147 offset:36896
	s_waitcnt lgkmcnt(4)
	v_mfma_f32_32x32x16_bf16 v[82:97], v[208:211], v[232:235], v[82:97]
	ds_read_b128 v[224:227], v148 offset:41504
	v_mfma_f32_32x32x16_bf16 v[66:81], v[212:215], v[232:235], v[66:81]
	ds_read_b128 v[228:231], v147 offset:41504
	s_waitcnt vmcnt(17)
	ds_write_b128 v149, v[130:133]
	s_waitcnt lgkmcnt(6)
	v_mfma_f32_32x32x16_bf16 v[50:65], v[208:211], v[236:239], v[50:65]
	ds_read_b128 v[232:235], v147 offset:46112
	v_mfma_f32_32x32x16_bf16 v[34:49], v[212:215], v[236:239], v[34:49]
	global_load_dwordx4 v[130:133], v153, s[74:75] offset:1536
	s_waitcnt lgkmcnt(6)
	v_mfma_f32_32x32x16_bf16 v[18:33], v[208:211], v[240:243], v[18:33]
	ds_read_b128 v[236:239], v147 offset:50720
	s_waitcnt vmcnt(17)
	ds_write_b128 v152, v[176:179]
	v_mfma_f32_32x32x16_bf16 v[2:17], v[212:215], v[240:243], v[2:17]
	s_waitcnt lgkmcnt(6)
	v_mfma_f32_32x32x16_bf16 v[98:113], v[216:219], v[244:247], v[98:113]
	ds_read_b128 v[208:211], v148 offset:36928
	global_load_dwordx4 v[176:179], v153, s[82:83] offset:1536
	s_waitcnt lgkmcnt(6)
	v_mfma_f32_32x32x16_bf16 v[114:129], v[224:227], v[244:247], v[114:129]
	ds_read_b128 v[240:243], v147 offset:36928
	s_waitcnt vmcnt(17)
	ds_write_b128 v149, v[134:137] offset:9216
	s_waitcnt lgkmcnt(7)
	v_mfma_f32_32x32x16_bf16 v[82:97], v[216:219], v[228:231], v[82:97]
	ds_read_b128 v[212:215], v148 offset:41536
	v_mfma_f32_32x32x16_bf16 v[66:81], v[224:227], v[228:231], v[66:81]
	ds_read_b128 v[244:247], v147 offset:41536
	global_load_dwordx4 v[134:137], v153, s[76:77] offset:1536
	s_waitcnt lgkmcnt(7)
	v_mfma_f32_32x32x16_bf16 v[50:65], v[216:219], v[232:235], v[50:65]
	ds_read_b128 v[228:231], v147 offset:46144
	s_waitcnt vmcnt(16)
	ds_write_b128 v152, v[180:183] offset:9216
	global_load_dword v155, v154, s[94:95] offset:384
	v_mfma_f32_32x32x16_bf16 v[34:49], v[224:227], v[232:235], v[34:49]
	s_waitcnt lgkmcnt(8)
	v_mfma_f32_32x32x16_bf16 v[18:33], v[216:219], v[236:239], v[18:33]
	ds_read_b128 v[232:235], v147 offset:50752
	global_load_dwordx4 v[180:183], v153, s[84:85] offset:1536
	v_mfma_f32_32x32x16_bf16 v[2:17], v[224:227], v[236:239], v[2:17]
	s_waitcnt vmcnt(17)
	ds_write_b128 v149, v[138:141] offset:18432
	s_waitcnt lgkmcnt(7)
	v_mfma_f32_32x32x16_bf16 v[98:113], v[208:211], v[240:243], v[98:113]
	ds_read_b128 v[216:219], v148 offset:36960
	s_waitcnt lgkmcnt(6)
	v_mfma_f32_32x32x16_bf16 v[114:129], v[212:215], v[240:243], v[114:129]
	ds_read_b128 v[236:239], v147 offset:36960
	global_load_dwordx4 v[138:141], v153, s[78:79] offset:1536
	s_waitcnt lgkmcnt(6)
	v_mfma_f32_32x32x16_bf16 v[82:97], v[208:211], v[244:247], v[82:97]
	ds_read_b128 v[224:227], v148 offset:41568
	s_waitcnt vmcnt(17)
	ds_write_b128 v152, v[184:187] offset:18432
	v_mfma_f32_32x32x16_bf16 v[66:81], v[212:215], v[244:247], v[66:81]
	ds_read_b128 v[240:243], v147 offset:41568
	s_waitcnt lgkmcnt(8)
	v_mfma_f32_32x32x16_bf16 v[50:65], v[208:211], v[228:231], v[50:65]
	ds_read_b128 v[244:247], v147 offset:46176
	global_load_dwordx4 v[184:187], v153, s[86:87] offset:1536
	v_mfma_f32_32x32x16_bf16 v[34:49], v[212:215], v[228:231], v[34:49]
	s_waitcnt vmcnt(17)
	ds_write_b128 v149, v[142:145] offset:27648
	s_waitcnt lgkmcnt(8)
	v_mfma_f32_32x32x16_bf16 v[18:33], v[208:211], v[232:235], v[18:33]
	ds_read_b128 v[228:231], v147 offset:50784
	v_mfma_f32_32x32x16_bf16 v[2:17], v[212:215], v[232:235], v[2:17]
	global_load_dwordx4 v[142:145], v153, s[80:81] offset:1536
	s_waitcnt lgkmcnt(6)
	v_mfma_f32_32x32x16_bf16 v[98:113], v[216:219], v[236:239], v[98:113]
	s_waitcnt vmcnt(17)
	ds_write_b128 v152, v[188:191] offset:27648
	s_waitcnt lgkmcnt(6)
	v_mfma_f32_32x32x16_bf16 v[114:129], v[224:227], v[236:239], v[114:129]
	s_waitcnt lgkmcnt(4)
	v_mfma_f32_32x32x16_bf16 v[82:97], v[216:219], v[240:243], v[82:97]
	global_load_dwordx4 v[188:191], v153, s[92:93] offset:1536
	v_mfma_f32_32x32x16_bf16 v[66:81], v[224:227], v[240:243], v[66:81]
	s_waitcnt lgkmcnt(3)
	v_mfma_f32_32x32x16_bf16 v[50:65], v[216:219], v[244:247], v[50:65]
	v_mfma_f32_32x32x16_bf16 v[34:49], v[224:227], v[244:247], v[34:49]
	s_waitcnt lgkmcnt(1)
	v_mfma_f32_32x32x16_bf16 v[18:33], v[216:219], v[228:231], v[18:33]
	v_mfma_f32_32x32x16_bf16 v[2:17], v[224:227], v[228:231], v[2:17]
	s_waitcnt lgkmcnt(0)
	s_barrier
;     ...
;   for (int kt = 0; kt < nk; ++kt) {
;     __syncthreads();
;     if (kt + 1 < nk) {
;       u16* aw = As0 + ((kt + 1) & 1) * 256 * LD;
;       u16* bw = Bs0 + ((kt + 1) & 1) * 256 * LD;
; #pragma unroll
;       for (int i = 0; i < 4; ++i) { *(u32x4*)(aw + (srow + 64 * i) * LD + skc * 8) = ra[i]; *(u32x4*)(bw + (srow + 64 * i) * LD + skc * 8) = rb[i]; }
;     }
;     if (kt + 2 < nk) {
; #pragma unroll
;       for (int i = 0; i < 4; ++i) { ra[i] = *(const u32x4*)(Ag + (size_t)(64 * i) * K + (kt + 2) * 64); rb[i] = *(const u32x4*)(Bg[i] + (kt + 2) * 64); }
;     }
;     __builtin_amdgcn_sched_barrier(0);
;     const u16* as = As0 + (kt & 1) * 256 * LD + (wr * 128 + l31) * LD + h * 8;
;     const u16* bs = Bs0 + (kt & 1) * 256 * LD + (wc * 64 + l31) * LD + h * 8;
;     if (domma)
; #pragma unroll
;     for (int ks = 0; ks < 4; ++ks) {
;       bf16x8 wf[2], xf[4];
; #pragma unroll
;       for (int ct = 0; ct < 2; ++ct) wf[ct] = *(const bf16x8*)(bs + ct * 32 * LD + ks * 16);
; #pragma unroll
;       for (int tt = 0; tt < 4; ++tt) xf[tt] = *(const bf16x8*)(as + tt * 32 * LD + ks * 16);
; #pragma unroll
;       for (int ct = 0; ct < 2; ++ct)
; #pragma unroll
;         for (int tt = 0; tt < 4; ++tt) acc[ct][tt] = __builtin_amdgcn_mfma_f32_32x32x16_bf16(wf[ct], xf[tt], acc[ct][tt], 0, 0, 0);
;     }
;     __builtin_amdgcn_sched_barrier(0);
;   }
	ds_read_b128 v[208:211], v148
	ds_read_b128 v[228:231], v147
	ds_read_b128 v[212:215], v148 offset:4608
	ds_read_b128 v[232:235], v147 offset:4608
	ds_read_b128 v[236:239], v147 offset:9216
	ds_read_b128 v[240:243], v147 offset:13824
	s_waitcnt lgkmcnt(4)
	v_mfma_f32_32x32x16_bf16 v[98:113], v[208:211], v[228:231], v[98:113]
	ds_read_b128 v[216:219], v148 offset:32
	s_waitcnt lgkmcnt(4)
	v_mfma_f32_32x32x16_bf16 v[114:129], v[212:215], v[228:231], v[114:129]
	ds_read_b128 v[244:247], v147 offset:32
	s_waitcnt lgkmcnt(4)
	v_mfma_f32_32x32x16_bf16 v[82:97], v[208:211], v[232:235], v[82:97]
	ds_read_b128 v[224:227], v148 offset:4640
	v_mfma_f32_32x32x16_bf16 v[66:81], v[212:215], v[232:235], v[66:81]
	ds_read_b128 v[228:231], v147 offset:4640
	s_waitcnt vmcnt(17)
	ds_write_b128 v149, v[160:163] offset:36864
	s_waitcnt lgkmcnt(6)
	v_mfma_f32_32x32x16_bf16 v[50:65], v[208:211], v[236:239], v[50:65]
	ds_read_b128 v[232:235], v147 offset:9248
	v_mfma_f32_32x32x16_bf16 v[34:49], v[212:215], v[236:239], v[34:49]
	global_load_dwordx4 v[160:163], v153, s[74:75] offset:1664
	s_waitcnt lgkmcnt(6)
	v_mfma_f32_32x32x16_bf16 v[18:33], v[208:211], v[240:243], v[18:33]
	ds_read_b128 v[236:239], v147 offset:13856
	s_waitcnt vmcnt(17)
	ds_write_b128 v152, v[192:195] offset:36864
	v_mfma_f32_32x32x16_bf16 v[2:17], v[212:215], v[240:243], v[2:17]
	s_waitcnt lgkmcnt(6)
	v_mfma_f32_32x32x16_bf16 v[98:113], v[216:219], v[244:247], v[98:113]
	ds_read_b128 v[208:211], v148 offset:64
	global_load_dwordx4 v[192:195], v153, s[82:83] offset:1664
	s_waitcnt lgkmcnt(6)
	v_mfma_f32_32x32x16_bf16 v[114:129], v[224:227], v[244:247], v[114:129]
	ds_read_b128 v[240:243], v147 offset:64
	s_waitcnt vmcnt(17)
	ds_write_b128 v149, v[164:167] offset:46080
	s_waitcnt lgkmcnt(7)
	v_mfma_f32_32x32x16_bf16 v[82:97], v[216:219], v[228:231], v[82:97]
	ds_read_b128 v[212:215], v148 offset:4672
	v_mfma_f32_32x32x16_bf16 v[66:81], v[224:227], v[228:231], v[66:81]
	ds_read_b128 v[244:247], v147 offset:4672
	global_load_dwordx4 v[164:167], v153, s[76:77] offset:1664
	s_waitcnt lgkmcnt(7)
	v_mfma_f32_32x32x16_bf16 v[50:65], v[216:219], v[232:235], v[50:65]
	ds_read_b128 v[228:231], v147 offset:9280
	s_waitcnt vmcnt(16)
	ds_write_b128 v152, v[196:199] offset:46080
	v_mfma_f32_32x32x16_bf16 v[34:49], v[224:227], v[232:235], v[34:49]
	s_waitcnt lgkmcnt(8)
	v_mfma_f32_32x32x16_bf16 v[18:33], v[216:219], v[236:239], v[18:33]
	ds_read_b128 v[232:235], v147 offset:13888
	global_load_dwordx4 v[196:199], v153, s[84:85] offset:1664
	v_mfma_f32_32x32x16_bf16 v[2:17], v[224:227], v[236:239], v[2:17]
	s_waitcnt vmcnt(16)
	ds_write_b128 v149, v[168:171] offset:55296
	s_waitcnt lgkmcnt(7)
	v_mfma_f32_32x32x16_bf16 v[98:113], v[208:211], v[240:243], v[98:113]
	ds_read_b128 v[216:219], v148 offset:96
	s_waitcnt lgkmcnt(6)
	v_mfma_f32_32x32x16_bf16 v[114:129], v[212:215], v[240:243], v[114:129]
	ds_read_b128 v[236:239], v147 offset:96
	global_load_dwordx4 v[168:171], v153, s[78:79] offset:1664
	s_waitcnt lgkmcnt(6)
	v_mfma_f32_32x32x16_bf16 v[82:97], v[208:211], v[244:247], v[82:97]
	ds_read_b128 v[224:227], v148 offset:4704
	s_waitcnt vmcnt(16)
	ds_write_b128 v152, v[200:203] offset:55296
	v_mfma_f32_32x32x16_bf16 v[66:81], v[212:215], v[244:247], v[66:81]
	ds_read_b128 v[240:243], v147 offset:4704
	s_waitcnt lgkmcnt(8)
	v_mfma_f32_32x32x16_bf16 v[50:65], v[208:211], v[228:231], v[50:65]
	ds_read_b128 v[244:247], v147 offset:9312
	global_load_dwordx4 v[200:203], v153, s[86:87] offset:1664
	v_mfma_f32_32x32x16_bf16 v[34:49], v[212:215], v[228:231], v[34:49]
	s_waitcnt vmcnt(16)
	ds_write_b128 v149, v[172:175] offset:64512
	s_waitcnt lgkmcnt(8)
	v_mfma_f32_32x32x16_bf16 v[18:33], v[208:211], v[232:235], v[18:33]
	ds_read_b128 v[228:231], v147 offset:13920
	v_mfma_f32_32x32x16_bf16 v[2:17], v[212:215], v[232:235], v[2:17]
	global_load_dwordx4 v[172:175], v153, s[80:81] offset:1664
	s_waitcnt lgkmcnt(6)
	v_mfma_f32_32x32x16_bf16 v[98:113], v[216:219], v[236:239], v[98:113]
	s_waitcnt vmcnt(16)
	ds_write_b128 v152, v[204:207] offset:64512
	s_waitcnt lgkmcnt(6)
	v_mfma_f32_32x32x16_bf16 v[114:129], v[224:227], v[236:239], v[114:129]
	s_waitcnt lgkmcnt(4)
	v_mfma_f32_32x32x16_bf16 v[82:97], v[216:219], v[240:243], v[82:97]
	global_load_dwordx4 v[204:207], v153, s[92:93] offset:1664
	v_mfma_f32_32x32x16_bf16 v[66:81], v[224:227], v[240:243], v[66:81]
	s_waitcnt lgkmcnt(3)
	v_mfma_f32_32x32x16_bf16 v[50:65], v[216:219], v[244:247], v[50:65]
	v_mfma_f32_32x32x16_bf16 v[34:49], v[224:227], v[244:247], v[34:49]
	s_waitcnt lgkmcnt(1)
	v_mfma_f32_32x32x16_bf16 v[18:33], v[216:219], v[228:231], v[18:33]
	v_mfma_f32_32x32x16_bf16 v[2:17], v[224:227], v[228:231], v[2:17]
	s_waitcnt lgkmcnt(0)
	s_barrier
;     ...
;   for (int kt = 0; kt < nk; ++kt) {
;     __syncthreads();
;     if (kt + 1 < nk) {
;       u16* aw = As0 + ((kt + 1) & 1) * 256 * LD;
;       u16* bw = Bs0 + ((kt + 1) & 1) * 256 * LD;
; #pragma unroll
;       for (int i = 0; i < 4; ++i) { *(u32x4*)(aw + (srow + 64 * i) * LD + skc * 8) = ra[i]; *(u32x4*)(bw + (srow + 64 * i) * LD + skc * 8) = rb[i]; }
;     }
;     if (kt + 2 < nk) {
; #pragma unroll
;       for (int i = 0; i < 4; ++i) { ra[i] = *(const u32x4*)(Ag + (size_t)(64 * i) * K + (kt + 2) * 64); rb[i] = *(const u32x4*)(Bg[i] + (kt + 2) * 64); }
;     }
;     __builtin_amdgcn_sched_barrier(0);
;     const u16* as = As0 + (kt & 1) * 256 * LD + (wr * 128 + l31) * LD + h * 8;
;     const u16* bs = Bs0 + (kt & 1) * 256 * LD + (wc * 64 + l31) * LD + h * 8;
;     if (domma)
; #pragma unroll
;     for (int ks = 0; ks < 4; ++ks) {
;       bf16x8 wf[2], xf[4];
; #pragma unroll
;       for (int ct = 0; ct < 2; ++ct) wf[ct] = *(const bf16x8*)(bs + ct * 32 * LD + ks * 16);
; #pragma unroll
;       for (int tt = 0; tt < 4; ++tt) xf[tt] = *(const bf16x8*)(as + tt * 32 * LD + ks * 16);
; #pragma unroll
;       for (int ct = 0; ct < 2; ++ct)
; #pragma unroll
;         for (int tt = 0; tt < 4; ++tt) acc[ct][tt] = __builtin_amdgcn_mfma_f32_32x32x16_bf16(wf[ct], xf[tt], acc[ct][tt], 0, 0, 0);
;     }
;     __builtin_amdgcn_sched_barrier(0);
;   }
	ds_read_b128 v[208:211], v148 offset:36864
	ds_read_b128 v[228:231], v147 offset:36864
	ds_read_b128 v[212:215], v148 offset:41472
	ds_read_b128 v[232:235], v147 offset:41472
	ds_read_b128 v[236:239], v147 offset:46080
	ds_read_b128 v[240:243], v147 offset:50688
	s_waitcnt lgkmcnt(4)
	v_mfma_f32_32x32x16_bf16 v[98:113], v[208:211], v[228:231], v[98:113]
	ds_read_b128 v[216:219], v148 offset:36896
	s_waitcnt lgkmcnt(4)
	v_mfma_f32_32x32x16_bf16 v[114:129], v[212:215], v[228:231], v[114:129]
	ds_read_b128 v[244:247], v147 offset:36896
	s_waitcnt lgkmcnt(4)
	v_mfma_f32_32x32x16_bf16 v[82:97], v[208:211], v[232:235], v[82:97]
	ds_read_b128 v[224:227], v148 offset:41504
	v_mfma_f32_32x32x16_bf16 v[66:81], v[212:215], v[232:235], v[66:81]
	ds_read_b128 v[228:231], v147 offset:41504
	s_waitcnt vmcnt(16)
	ds_write_b128 v149, v[130:133]
	s_waitcnt lgkmcnt(6)
	v_mfma_f32_32x32x16_bf16 v[50:65], v[208:211], v[236:239], v[50:65]
	ds_read_b128 v[232:235], v147 offset:46112
	v_mfma_f32_32x32x16_bf16 v[34:49], v[212:215], v[236:239], v[34:49]
	global_load_dwordx4 v[130:133], v153, s[74:75] offset:1792
	s_waitcnt lgkmcnt(6)
	v_mfma_f32_32x32x16_bf16 v[18:33], v[208:211], v[240:243], v[18:33]
	ds_read_b128 v[236:239], v147 offset:50720
	s_waitcnt vmcnt(16)
	ds_write_b128 v152, v[176:179]
	v_mfma_f32_32x32x16_bf16 v[2:17], v[212:215], v[240:243], v[2:17]
	s_waitcnt lgkmcnt(6)
	v_mfma_f32_32x32x16_bf16 v[98:113], v[216:219], v[244:247], v[98:113]
	ds_read_b128 v[208:211], v148 offset:36928
	global_load_dwordx4 v[176:179], v153, s[82:83] offset:1792
	s_waitcnt lgkmcnt(6)
	v_mfma_f32_32x32x16_bf16 v[114:129], v[224:227], v[244:247], v[114:129]
	ds_read_b128 v[240:243], v147 offset:36928
	s_waitcnt vmcnt(16)
	ds_write_b128 v149, v[134:137] offset:9216
	s_waitcnt lgkmcnt(7)
	v_mfma_f32_32x32x16_bf16 v[82:97], v[216:219], v[228:231], v[82:97]
	ds_read_b128 v[212:215], v148 offset:41536
	v_mfma_f32_32x32x16_bf16 v[66:81], v[224:227], v[228:231], v[66:81]
	ds_read_b128 v[244:247], v147 offset:41536
	global_load_dwordx4 v[134:137], v153, s[76:77] offset:1792
	s_waitcnt lgkmcnt(7)
	v_mfma_f32_32x32x16_bf16 v[50:65], v[216:219], v[232:235], v[50:65]
	ds_read_b128 v[228:231], v147 offset:46144
	s_waitcnt vmcnt(15)
	ds_write_b128 v152, v[180:183] offset:9216
	v_mfma_f32_32x32x16_bf16 v[34:49], v[224:227], v[232:235], v[34:49]
	s_waitcnt lgkmcnt(8)
	v_mfma_f32_32x32x16_bf16 v[18:33], v[216:219], v[236:239], v[18:33]
	ds_read_b128 v[232:235], v147 offset:50752
	global_load_dwordx4 v[180:183], v153, s[84:85] offset:1792
	v_mfma_f32_32x32x16_bf16 v[2:17], v[224:227], v[236:239], v[2:17]
	s_waitcnt vmcnt(15)
	ds_write_b128 v149, v[138:141] offset:18432
	s_waitcnt lgkmcnt(7)
	v_mfma_f32_32x32x16_bf16 v[98:113], v[208:211], v[240:243], v[98:113]
	ds_read_b128 v[216:219], v148 offset:36960
	s_waitcnt lgkmcnt(6)
	v_mfma_f32_32x32x16_bf16 v[114:129], v[212:215], v[240:243], v[114:129]
	ds_read_b128 v[236:239], v147 offset:36960
	global_load_dwordx4 v[138:141], v153, s[78:79] offset:1792
	s_waitcnt lgkmcnt(6)
	v_mfma_f32_32x32x16_bf16 v[82:97], v[208:211], v[244:247], v[82:97]
	ds_read_b128 v[224:227], v148 offset:41568
	s_waitcnt vmcnt(15)
	ds_write_b128 v152, v[184:187] offset:18432
	v_mfma_f32_32x32x16_bf16 v[66:81], v[212:215], v[244:247], v[66:81]
	ds_read_b128 v[240:243], v147 offset:41568
	s_waitcnt lgkmcnt(8)
	v_mfma_f32_32x32x16_bf16 v[50:65], v[208:211], v[228:231], v[50:65]
	ds_read_b128 v[244:247], v147 offset:46176
	global_load_dwordx4 v[184:187], v153, s[86:87] offset:1792
	v_mfma_f32_32x32x16_bf16 v[34:49], v[212:215], v[228:231], v[34:49]
	s_waitcnt vmcnt(15)
	ds_write_b128 v149, v[142:145] offset:27648
	s_waitcnt lgkmcnt(8)
	v_mfma_f32_32x32x16_bf16 v[18:33], v[208:211], v[232:235], v[18:33]
	ds_read_b128 v[228:231], v147 offset:50784
	v_mfma_f32_32x32x16_bf16 v[2:17], v[212:215], v[232:235], v[2:17]
	global_load_dwordx4 v[142:145], v153, s[80:81] offset:1792
	s_waitcnt lgkmcnt(6)
	v_mfma_f32_32x32x16_bf16 v[98:113], v[216:219], v[236:239], v[98:113]
	s_waitcnt vmcnt(15)
	ds_write_b128 v152, v[188:191] offset:27648
	s_waitcnt lgkmcnt(6)
	v_mfma_f32_32x32x16_bf16 v[114:129], v[224:227], v[236:239], v[114:129]
	s_waitcnt lgkmcnt(4)
	v_mfma_f32_32x32x16_bf16 v[82:97], v[216:219], v[240:243], v[82:97]
	global_load_dwordx4 v[188:191], v153, s[92:93] offset:1792
	v_mfma_f32_32x32x16_bf16 v[66:81], v[224:227], v[240:243], v[66:81]
	s_waitcnt lgkmcnt(3)
	v_mfma_f32_32x32x16_bf16 v[50:65], v[216:219], v[244:247], v[50:65]
	v_mfma_f32_32x32x16_bf16 v[34:49], v[224:227], v[244:247], v[34:49]
	s_waitcnt lgkmcnt(1)
	v_mfma_f32_32x32x16_bf16 v[18:33], v[216:219], v[228:231], v[18:33]
	v_mfma_f32_32x32x16_bf16 v[2:17], v[224:227], v[228:231], v[2:17]
	s_waitcnt lgkmcnt(0)
	s_barrier
;     ...
;   for (int kt = 0; kt < nk; ++kt) {
;     __syncthreads();
;     if (kt + 1 < nk) {
;       u16* aw = As0 + ((kt + 1) & 1) * 256 * LD;
;       u16* bw = Bs0 + ((kt + 1) & 1) * 256 * LD;
; #pragma unroll
;       for (int i = 0; i < 4; ++i) { *(u32x4*)(aw + (srow + 64 * i) * LD + skc * 8) = ra[i]; *(u32x4*)(bw + (srow + 64 * i) * LD + skc * 8) = rb[i]; }
;     }
;     if (kt + 2 < nk) {
; #pragma unroll
;       for (int i = 0; i < 4; ++i) { ra[i] = *(const u32x4*)(Ag + (size_t)(64 * i) * K + (kt + 2) * 64); rb[i] = *(const u32x4*)(Bg[i] + (kt + 2) * 64); }
;     }
;     __builtin_amdgcn_sched_barrier(0);
;     const u16* as = As0 + (kt & 1) * 256 * LD + (wr * 128 + l31) * LD + h * 8;
;     const u16* bs = Bs0 + (kt & 1) * 256 * LD + (wc * 64 + l31) * LD + h * 8;
;     if (domma)
; #pragma unroll
;     for (int ks = 0; ks < 4; ++ks) {
;       bf16x8 wf[2], xf[4];
; #pragma unroll
;       for (int ct = 0; ct < 2; ++ct) wf[ct] = *(const bf16x8*)(bs + ct * 32 * LD + ks * 16);
; #pragma unroll
;       for (int tt = 0; tt < 4; ++tt) xf[tt] = *(const bf16x8*)(as + tt * 32 * LD + ks * 16);
; #pragma unroll
;       for (int ct = 0; ct < 2; ++ct)
; #pragma unroll
;         for (int tt = 0; tt < 4; ++tt) acc[ct][tt] = __builtin_amdgcn_mfma_f32_32x32x16_bf16(wf[ct], xf[tt], acc[ct][tt], 0, 0, 0);
;     }
;     __builtin_amdgcn_sched_barrier(0);
;   }
	ds_read_b128 v[208:211], v148
	ds_read_b128 v[228:231], v147
	ds_read_b128 v[212:215], v148 offset:4608
	ds_read_b128 v[232:235], v147 offset:4608
	ds_read_b128 v[236:239], v147 offset:9216
	ds_read_b128 v[240:243], v147 offset:13824
	s_waitcnt lgkmcnt(4)
	v_mfma_f32_32x32x16_bf16 v[98:113], v[208:211], v[228:231], v[98:113]
	ds_read_b128 v[216:219], v148 offset:32
	s_waitcnt lgkmcnt(4)
	v_mfma_f32_32x32x16_bf16 v[114:129], v[212:215], v[228:231], v[114:129]
	ds_read_b128 v[244:247], v147 offset:32
	s_waitcnt lgkmcnt(4)
	v_mfma_f32_32x32x16_bf16 v[82:97], v[208:211], v[232:235], v[82:97]
	ds_read_b128 v[224:227], v148 offset:4640
	v_mfma_f32_32x32x16_bf16 v[66:81], v[212:215], v[232:235], v[66:81]
	ds_read_b128 v[228:231], v147 offset:4640
	s_waitcnt vmcnt(15)
	ds_write_b128 v149, v[160:163] offset:36864
	s_waitcnt lgkmcnt(6)
	v_mfma_f32_32x32x16_bf16 v[50:65], v[208:211], v[236:239], v[50:65]
	ds_read_b128 v[232:235], v147 offset:9248
	v_mfma_f32_32x32x16_bf16 v[34:49], v[212:215], v[236:239], v[34:49]
	global_load_dwordx4 v[160:163], v153, s[74:75] offset:1920
	s_waitcnt lgkmcnt(6)
	v_mfma_f32_32x32x16_bf16 v[18:33], v[208:211], v[240:243], v[18:33]
	ds_read_b128 v[236:239], v147 offset:13856
	s_waitcnt vmcnt(15)
	ds_write_b128 v152, v[192:195] offset:36864
	v_mfma_f32_32x32x16_bf16 v[2:17], v[212:215], v[240:243], v[2:17]
	s_waitcnt lgkmcnt(6)
	v_mfma_f32_32x32x16_bf16 v[98:113], v[216:219], v[244:247], v[98:113]
	ds_read_b128 v[208:211], v148 offset:64
	global_load_dwordx4 v[192:195], v153, s[82:83] offset:1920
	s_waitcnt lgkmcnt(6)
	v_mfma_f32_32x32x16_bf16 v[114:129], v[224:227], v[244:247], v[114:129]
	ds_read_b128 v[240:243], v147 offset:64
	s_waitcnt vmcnt(15)
	ds_write_b128 v149, v[164:167] offset:46080
	s_waitcnt lgkmcnt(7)
	v_mfma_f32_32x32x16_bf16 v[82:97], v[216:219], v[228:231], v[82:97]
	ds_read_b128 v[212:215], v148 offset:4672
	v_mfma_f32_32x32x16_bf16 v[66:81], v[224:227], v[228:231], v[66:81]
	ds_read_b128 v[244:247], v147 offset:4672
	global_load_dwordx4 v[164:167], v153, s[76:77] offset:1920
	s_waitcnt lgkmcnt(7)
	v_mfma_f32_32x32x16_bf16 v[50:65], v[216:219], v[232:235], v[50:65]
	ds_read_b128 v[228:231], v147 offset:9280
	s_waitcnt vmcnt(15)
	ds_write_b128 v152, v[196:199] offset:46080
	v_mfma_f32_32x32x16_bf16 v[34:49], v[224:227], v[232:235], v[34:49]
	s_waitcnt lgkmcnt(8)
	v_mfma_f32_32x32x16_bf16 v[18:33], v[216:219], v[236:239], v[18:33]
	ds_read_b128 v[232:235], v147 offset:13888
	global_load_dwordx4 v[196:199], v153, s[84:85] offset:1920
	v_mfma_f32_32x32x16_bf16 v[2:17], v[224:227], v[236:239], v[2:17]
	s_waitcnt vmcnt(15)
	ds_write_b128 v149, v[168:171] offset:55296
	s_waitcnt lgkmcnt(7)
	v_mfma_f32_32x32x16_bf16 v[98:113], v[208:211], v[240:243], v[98:113]
	ds_read_b128 v[216:219], v148 offset:96
	s_waitcnt lgkmcnt(6)
	v_mfma_f32_32x32x16_bf16 v[114:129], v[212:215], v[240:243], v[114:129]
	ds_read_b128 v[236:239], v147 offset:96
	global_load_dwordx4 v[168:171], v153, s[78:79] offset:1920
	s_waitcnt lgkmcnt(6)
	v_mfma_f32_32x32x16_bf16 v[82:97], v[208:211], v[244:247], v[82:97]
	ds_read_b128 v[224:227], v148 offset:4704
	s_waitcnt vmcnt(15)
	ds_write_b128 v152, v[200:203] offset:55296
	v_mfma_f32_32x32x16_bf16 v[66:81], v[212:215], v[244:247], v[66:81]
	ds_read_b128 v[240:243], v147 offset:4704
	s_waitcnt lgkmcnt(8)
	v_mfma_f32_32x32x16_bf16 v[50:65], v[208:211], v[228:231], v[50:65]
	ds_read_b128 v[244:247], v147 offset:9312
	global_load_dwordx4 v[200:203], v153, s[86:87] offset:1920
	v_mfma_f32_32x32x16_bf16 v[34:49], v[212:215], v[228:231], v[34:49]
	s_waitcnt vmcnt(15)
	ds_write_b128 v149, v[172:175] offset:64512
	s_waitcnt lgkmcnt(8)
	v_mfma_f32_32x32x16_bf16 v[18:33], v[208:211], v[232:235], v[18:33]
	ds_read_b128 v[228:231], v147 offset:13920
	v_mfma_f32_32x32x16_bf16 v[2:17], v[212:215], v[232:235], v[2:17]
	global_load_dwordx4 v[172:175], v153, s[80:81] offset:1920
	s_waitcnt lgkmcnt(6)
	v_mfma_f32_32x32x16_bf16 v[98:113], v[216:219], v[236:239], v[98:113]
	s_waitcnt vmcnt(15)
	ds_write_b128 v152, v[204:207] offset:64512
	s_waitcnt lgkmcnt(6)
	v_mfma_f32_32x32x16_bf16 v[114:129], v[224:227], v[236:239], v[114:129]
	s_waitcnt lgkmcnt(4)
	v_mfma_f32_32x32x16_bf16 v[82:97], v[216:219], v[240:243], v[82:97]
	global_load_dwordx4 v[204:207], v153, s[92:93] offset:1920
	v_mfma_f32_32x32x16_bf16 v[66:81], v[224:227], v[240:243], v[66:81]
	s_waitcnt lgkmcnt(3)
	v_mfma_f32_32x32x16_bf16 v[50:65], v[216:219], v[244:247], v[50:65]
	v_mfma_f32_32x32x16_bf16 v[34:49], v[224:227], v[244:247], v[34:49]
	s_waitcnt lgkmcnt(1)
	v_mfma_f32_32x32x16_bf16 v[18:33], v[216:219], v[228:231], v[18:33]
	v_mfma_f32_32x32x16_bf16 v[2:17], v[224:227], v[228:231], v[2:17]
	s_waitcnt lgkmcnt(0)
	s_barrier
;     ...
;   for (int kt = 0; kt < nk; ++kt) {
;     __syncthreads();
;     if (kt + 1 < nk) {
;       u16* aw = As0 + ((kt + 1) & 1) * 256 * LD;
;       u16* bw = Bs0 + ((kt + 1) & 1) * 256 * LD;
; #pragma unroll
;       for (int i = 0; i < 4; ++i) { *(u32x4*)(aw + (srow + 64 * i) * LD + skc * 8) = ra[i]; *(u32x4*)(bw + (srow + 64 * i) * LD + skc * 8) = rb[i]; }
;     }
;     if (kt + 2 < nk) {
; #pragma unroll
;       for (int i = 0; i < 4; ++i) { ra[i] = *(const u32x4*)(Ag + (size_t)(64 * i) * K + (kt + 2) * 64); rb[i] = *(const u32x4*)(Bg[i] + (kt + 2) * 64); }
;     }
;     __builtin_amdgcn_sched_barrier(0);
;     const u16* as = As0 + (kt & 1) * 256 * LD + (wr * 128 + l31) * LD + h * 8;
;     const u16* bs = Bs0 + (kt & 1) * 256 * LD + (wc * 64 + l31) * LD + h * 8;
;     if (domma)
; #pragma unroll
;     for (int ks = 0; ks < 4; ++ks) {
;       bf16x8 wf[2], xf[4];
; #pragma unroll
;       for (int ct = 0; ct < 2; ++ct) wf[ct] = *(const bf16x8*)(bs + ct * 32 * LD + ks * 16);
; #pragma unroll
;       for (int tt = 0; tt < 4; ++tt) xf[tt] = *(const bf16x8*)(as + tt * 32 * LD + ks * 16);
; #pragma unroll
;       for (int ct = 0; ct < 2; ++ct)
; #pragma unroll
;         for (int tt = 0; tt < 4; ++tt) acc[ct][tt] = __builtin_amdgcn_mfma_f32_32x32x16_bf16(wf[ct], xf[tt], acc[ct][tt], 0, 0, 0);
;     }
;     __builtin_amdgcn_sched_barrier(0);
;   }
	ds_read_b128 v[208:211], v148 offset:36864
	ds_read_b128 v[228:231], v147 offset:36864
	ds_read_b128 v[212:215], v148 offset:41472
	ds_read_b128 v[232:235], v147 offset:41472
	ds_read_b128 v[236:239], v147 offset:46080
	ds_read_b128 v[240:243], v147 offset:50688
	s_waitcnt lgkmcnt(4)
	v_mfma_f32_32x32x16_bf16 v[98:113], v[208:211], v[228:231], v[98:113]
	ds_read_b128 v[216:219], v148 offset:36896
	s_waitcnt lgkmcnt(4)
	v_mfma_f32_32x32x16_bf16 v[114:129], v[212:215], v[228:231], v[114:129]
	ds_read_b128 v[244:247], v147 offset:36896
	s_waitcnt lgkmcnt(4)
	v_mfma_f32_32x32x16_bf16 v[82:97], v[208:211], v[232:235], v[82:97]
	ds_read_b128 v[224:227], v148 offset:41504
	v_mfma_f32_32x32x16_bf16 v[66:81], v[212:215], v[232:235], v[66:81]
	ds_read_b128 v[228:231], v147 offset:41504
	s_waitcnt vmcnt(15)
	ds_write_b128 v149, v[130:133]
	s_waitcnt lgkmcnt(6)
	v_mfma_f32_32x32x16_bf16 v[50:65], v[208:211], v[236:239], v[50:65]
	ds_read_b128 v[232:235], v147 offset:46112
	v_mfma_f32_32x32x16_bf16 v[34:49], v[212:215], v[236:239], v[34:49]
	s_waitcnt lgkmcnt(6)
	v_mfma_f32_32x32x16_bf16 v[18:33], v[208:211], v[240:243], v[18:33]
	ds_read_b128 v[236:239], v147 offset:50720
	s_waitcnt vmcnt(14)
	ds_write_b128 v152, v[176:179]
	v_mfma_f32_32x32x16_bf16 v[2:17], v[212:215], v[240:243], v[2:17]
	s_waitcnt lgkmcnt(6)
	v_mfma_f32_32x32x16_bf16 v[98:113], v[216:219], v[244:247], v[98:113]
	ds_read_b128 v[208:211], v148 offset:36928
	s_waitcnt lgkmcnt(6)
	v_mfma_f32_32x32x16_bf16 v[114:129], v[224:227], v[244:247], v[114:129]
	ds_read_b128 v[240:243], v147 offset:36928
	s_waitcnt vmcnt(13)
	ds_write_b128 v149, v[134:137] offset:9216
	s_waitcnt lgkmcnt(7)
	v_mfma_f32_32x32x16_bf16 v[82:97], v[216:219], v[228:231], v[82:97]
	ds_read_b128 v[212:215], v148 offset:41536
	v_mfma_f32_32x32x16_bf16 v[66:81], v[224:227], v[228:231], v[66:81]
	ds_read_b128 v[244:247], v147 offset:41536
	s_waitcnt lgkmcnt(7)
	v_mfma_f32_32x32x16_bf16 v[50:65], v[216:219], v[232:235], v[50:65]
	ds_read_b128 v[228:231], v147 offset:46144
	s_waitcnt vmcnt(12)
	ds_write_b128 v152, v[180:183] offset:9216
	v_mfma_f32_32x32x16_bf16 v[34:49], v[224:227], v[232:235], v[34:49]
	s_waitcnt lgkmcnt(8)
	v_mfma_f32_32x32x16_bf16 v[18:33], v[216:219], v[236:239], v[18:33]
	ds_read_b128 v[232:235], v147 offset:50752
	v_mfma_f32_32x32x16_bf16 v[2:17], v[224:227], v[236:239], v[2:17]
	s_waitcnt vmcnt(11)
	ds_write_b128 v149, v[138:141] offset:18432
	s_waitcnt lgkmcnt(7)
	v_mfma_f32_32x32x16_bf16 v[98:113], v[208:211], v[240:243], v[98:113]
	ds_read_b128 v[216:219], v148 offset:36960
	s_waitcnt lgkmcnt(6)
	v_mfma_f32_32x32x16_bf16 v[114:129], v[212:215], v[240:243], v[114:129]
	ds_read_b128 v[236:239], v147 offset:36960
	s_waitcnt lgkmcnt(6)
	v_mfma_f32_32x32x16_bf16 v[82:97], v[208:211], v[244:247], v[82:97]
	ds_read_b128 v[224:227], v148 offset:41568
	s_waitcnt vmcnt(10)
	ds_write_b128 v152, v[184:187] offset:18432
	v_mfma_f32_32x32x16_bf16 v[66:81], v[212:215], v[244:247], v[66:81]
	ds_read_b128 v[240:243], v147 offset:41568
	s_waitcnt lgkmcnt(8)
	v_mfma_f32_32x32x16_bf16 v[50:65], v[208:211], v[228:231], v[50:65]
	ds_read_b128 v[244:247], v147 offset:46176
	v_mfma_f32_32x32x16_bf16 v[34:49], v[212:215], v[228:231], v[34:49]
	s_waitcnt vmcnt(9)
	ds_write_b128 v149, v[142:145] offset:27648
	s_waitcnt lgkmcnt(8)
	v_mfma_f32_32x32x16_bf16 v[18:33], v[208:211], v[232:235], v[18:33]
	ds_read_b128 v[228:231], v147 offset:50784
	v_mfma_f32_32x32x16_bf16 v[2:17], v[212:215], v[232:235], v[2:17]
	s_waitcnt lgkmcnt(6)
	v_mfma_f32_32x32x16_bf16 v[98:113], v[216:219], v[236:239], v[98:113]
	s_waitcnt vmcnt(8)
	ds_write_b128 v152, v[188:191] offset:27648
	s_waitcnt lgkmcnt(6)
	v_mfma_f32_32x32x16_bf16 v[114:129], v[224:227], v[236:239], v[114:129]
	s_waitcnt lgkmcnt(4)
	v_mfma_f32_32x32x16_bf16 v[82:97], v[216:219], v[240:243], v[82:97]
	v_mfma_f32_32x32x16_bf16 v[66:81], v[224:227], v[240:243], v[66:81]
	s_waitcnt lgkmcnt(3)
	v_mfma_f32_32x32x16_bf16 v[50:65], v[216:219], v[244:247], v[50:65]
	v_mfma_f32_32x32x16_bf16 v[34:49], v[224:227], v[244:247], v[34:49]
	s_waitcnt lgkmcnt(1)
	v_mfma_f32_32x32x16_bf16 v[18:33], v[216:219], v[228:231], v[18:33]
	v_mfma_f32_32x32x16_bf16 v[2:17], v[224:227], v[228:231], v[2:17]
	s_waitcnt lgkmcnt(0)
	s_barrier
;     ...
;   for (int kt = 0; kt < nk; ++kt) {
;     __syncthreads();
;     if (kt + 1 < nk) {
;       u16* aw = As0 + ((kt + 1) & 1) * 256 * LD;
;       u16* bw = Bs0 + ((kt + 1) & 1) * 256 * LD;
; #pragma unroll
;       for (int i = 0; i < 4; ++i) { *(u32x4*)(aw + (srow + 64 * i) * LD + skc * 8) = ra[i]; *(u32x4*)(bw + (srow + 64 * i) * LD + skc * 8) = rb[i]; }
;     }
;     if (kt + 2 < nk) {
; #pragma unroll
;       for (int i = 0; i < 4; ++i) { ra[i] = *(const u32x4*)(Ag + (size_t)(64 * i) * K + (kt + 2) * 64); rb[i] = *(const u32x4*)(Bg[i] + (kt + 2) * 64); }
;     }
;     __builtin_amdgcn_sched_barrier(0);
;     const u16* as = As0 + (kt & 1) * 256 * LD + (wr * 128 + l31) * LD + h * 8;
;     const u16* bs = Bs0 + (kt & 1) * 256 * LD + (wc * 64 + l31) * LD + h * 8;
;     if (domma)
; #pragma unroll
;     for (int ks = 0; ks < 4; ++ks) {
;       bf16x8 wf[2], xf[4];
; #pragma unroll
;       for (int ct = 0; ct < 2; ++ct) wf[ct] = *(const bf16x8*)(bs + ct * 32 * LD + ks * 16);
; #pragma unroll
;       for (int tt = 0; tt < 4; ++tt) xf[tt] = *(const bf16x8*)(as + tt * 32 * LD + ks * 16);
; #pragma unroll
;       for (int ct = 0; ct < 2; ++ct)
; #pragma unroll
;         for (int tt = 0; tt < 4; ++tt) acc[ct][tt] = __builtin_amdgcn_mfma_f32_32x32x16_bf16(wf[ct], xf[tt], acc[ct][tt], 0, 0, 0);
;     }
;     __builtin_amdgcn_sched_barrier(0);
;   }
	ds_read_b128 v[208:211], v148
	ds_read_b128 v[228:231], v147
	ds_read_b128 v[212:215], v148 offset:4608
	ds_read_b128 v[232:235], v147 offset:4608
	ds_read_b128 v[236:239], v147 offset:9216
	ds_read_b128 v[240:243], v147 offset:13824
	s_waitcnt lgkmcnt(4)
	v_mfma_f32_32x32x16_bf16 v[98:113], v[208:211], v[228:231], v[98:113]
	ds_read_b128 v[216:219], v148 offset:32
	s_waitcnt lgkmcnt(4)
	v_mfma_f32_32x32x16_bf16 v[114:129], v[212:215], v[228:231], v[114:129]
	ds_read_b128 v[244:247], v147 offset:32
	s_waitcnt lgkmcnt(4)
	v_mfma_f32_32x32x16_bf16 v[82:97], v[208:211], v[232:235], v[82:97]
	ds_read_b128 v[224:227], v148 offset:4640
	v_mfma_f32_32x32x16_bf16 v[66:81], v[212:215], v[232:235], v[66:81]
	ds_read_b128 v[228:231], v147 offset:4640
	s_waitcnt vmcnt(7)
	ds_write_b128 v149, v[160:163] offset:36864
	s_waitcnt lgkmcnt(6)
	v_mfma_f32_32x32x16_bf16 v[50:65], v[208:211], v[236:239], v[50:65]
	ds_read_b128 v[232:235], v147 offset:9248
	v_mfma_f32_32x32x16_bf16 v[34:49], v[212:215], v[236:239], v[34:49]
	s_waitcnt lgkmcnt(6)
	v_mfma_f32_32x32x16_bf16 v[18:33], v[208:211], v[240:243], v[18:33]
	ds_read_b128 v[236:239], v147 offset:13856
	s_waitcnt vmcnt(6)
	ds_write_b128 v152, v[192:195] offset:36864
	v_mfma_f32_32x32x16_bf16 v[2:17], v[212:215], v[240:243], v[2:17]
	s_waitcnt lgkmcnt(6)
	v_mfma_f32_32x32x16_bf16 v[98:113], v[216:219], v[244:247], v[98:113]
	ds_read_b128 v[208:211], v148 offset:64
	s_waitcnt lgkmcnt(6)
	v_mfma_f32_32x32x16_bf16 v[114:129], v[224:227], v[244:247], v[114:129]
	ds_read_b128 v[240:243], v147 offset:64
	s_waitcnt vmcnt(5)
	ds_write_b128 v149, v[164:167] offset:46080
	s_waitcnt lgkmcnt(7)
	v_mfma_f32_32x32x16_bf16 v[82:97], v[216:219], v[228:231], v[82:97]
	ds_read_b128 v[212:215], v148 offset:4672
	v_mfma_f32_32x32x16_bf16 v[66:81], v[224:227], v[228:231], v[66:81]
	ds_read_b128 v[244:247], v147 offset:4672
	s_waitcnt lgkmcnt(7)
	v_mfma_f32_32x32x16_bf16 v[50:65], v[216:219], v[232:235], v[50:65]
	ds_read_b128 v[228:231], v147 offset:9280
	s_waitcnt vmcnt(4)
	ds_write_b128 v152, v[196:199] offset:46080
	v_mfma_f32_32x32x16_bf16 v[34:49], v[224:227], v[232:235], v[34:49]
	s_waitcnt lgkmcnt(8)
	v_mfma_f32_32x32x16_bf16 v[18:33], v[216:219], v[236:239], v[18:33]
	ds_read_b128 v[232:235], v147 offset:13888
	v_mfma_f32_32x32x16_bf16 v[2:17], v[224:227], v[236:239], v[2:17]
	s_waitcnt vmcnt(3)
	ds_write_b128 v149, v[168:171] offset:55296
	s_waitcnt lgkmcnt(7)
	v_mfma_f32_32x32x16_bf16 v[98:113], v[208:211], v[240:243], v[98:113]
	ds_read_b128 v[216:219], v148 offset:96
	s_waitcnt lgkmcnt(6)
	v_mfma_f32_32x32x16_bf16 v[114:129], v[212:215], v[240:243], v[114:129]
	ds_read_b128 v[236:239], v147 offset:96
	s_waitcnt lgkmcnt(6)
	v_mfma_f32_32x32x16_bf16 v[82:97], v[208:211], v[244:247], v[82:97]
	ds_read_b128 v[224:227], v148 offset:4704
	s_waitcnt vmcnt(2)
	ds_write_b128 v152, v[200:203] offset:55296
	v_mfma_f32_32x32x16_bf16 v[66:81], v[212:215], v[244:247], v[66:81]
	ds_read_b128 v[240:243], v147 offset:4704
	s_waitcnt lgkmcnt(8)
	v_mfma_f32_32x32x16_bf16 v[50:65], v[208:211], v[228:231], v[50:65]
	ds_read_b128 v[244:247], v147 offset:9312
	v_mfma_f32_32x32x16_bf16 v[34:49], v[212:215], v[228:231], v[34:49]
	s_waitcnt vmcnt(1)
	ds_write_b128 v149, v[172:175] offset:64512
	s_waitcnt lgkmcnt(8)
	v_mfma_f32_32x32x16_bf16 v[18:33], v[208:211], v[232:235], v[18:33]
	ds_read_b128 v[228:231], v147 offset:13920
	v_mfma_f32_32x32x16_bf16 v[2:17], v[212:215], v[232:235], v[2:17]
	s_waitcnt lgkmcnt(6)
	v_mfma_f32_32x32x16_bf16 v[98:113], v[216:219], v[236:239], v[98:113]
	s_waitcnt vmcnt(0)
	ds_write_b128 v152, v[204:207] offset:64512
	s_waitcnt lgkmcnt(6)
	v_mfma_f32_32x32x16_bf16 v[114:129], v[224:227], v[236:239], v[114:129]
	s_waitcnt lgkmcnt(4)
	v_mfma_f32_32x32x16_bf16 v[82:97], v[216:219], v[240:243], v[82:97]
	v_mfma_f32_32x32x16_bf16 v[66:81], v[224:227], v[240:243], v[66:81]
	s_waitcnt lgkmcnt(3)
	v_mfma_f32_32x32x16_bf16 v[50:65], v[216:219], v[244:247], v[50:65]
	v_mfma_f32_32x32x16_bf16 v[34:49], v[224:227], v[244:247], v[34:49]
	s_waitcnt lgkmcnt(1)
	v_mfma_f32_32x32x16_bf16 v[18:33], v[216:219], v[228:231], v[18:33]
	v_mfma_f32_32x32x16_bf16 v[2:17], v[224:227], v[228:231], v[2:17]
	s_waitcnt lgkmcnt(0)
	s_barrier
	ds_read_b128 v[208:211], v148 offset:36864
	ds_read_b128 v[228:231], v147 offset:36864
	ds_read_b128 v[212:215], v148 offset:41472
	ds_read_b128 v[232:235], v147 offset:41472
	ds_read_b128 v[236:239], v147 offset:46080
	ds_read_b128 v[240:243], v147 offset:50688
	s_waitcnt lgkmcnt(4)
	v_mfma_f32_32x32x16_bf16 v[98:113], v[208:211], v[228:231], v[98:113]
	ds_read_b128 v[216:219], v148 offset:36896
	s_waitcnt lgkmcnt(4)
	v_mfma_f32_32x32x16_bf16 v[114:129], v[212:215], v[228:231], v[114:129]
	ds_read_b128 v[244:247], v147 offset:36896
	s_waitcnt lgkmcnt(4)
	v_mfma_f32_32x32x16_bf16 v[82:97], v[208:211], v[232:235], v[82:97]
	ds_read_b128 v[224:227], v148 offset:41504
	v_mfma_f32_32x32x16_bf16 v[66:81], v[212:215], v[232:235], v[66:81]
	ds_read_b128 v[228:231], v147 offset:41504
	s_waitcnt lgkmcnt(5)
	v_mfma_f32_32x32x16_bf16 v[50:65], v[208:211], v[236:239], v[50:65]
	ds_read_b128 v[232:235], v147 offset:46112
	v_mfma_f32_32x32x16_bf16 v[34:49], v[212:215], v[236:239], v[34:49]
	s_waitcnt lgkmcnt(5)
	v_mfma_f32_32x32x16_bf16 v[18:33], v[208:211], v[240:243], v[18:33]
	ds_read_b128 v[236:239], v147 offset:50720
	v_mfma_f32_32x32x16_bf16 v[2:17], v[212:215], v[240:243], v[2:17]
	s_waitcnt lgkmcnt(4)
	v_mfma_f32_32x32x16_bf16 v[98:113], v[216:219], v[244:247], v[98:113]
	ds_read_b128 v[208:211], v148 offset:36928
	s_waitcnt lgkmcnt(4)
	v_mfma_f32_32x32x16_bf16 v[114:129], v[224:227], v[244:247], v[114:129]
	ds_read_b128 v[240:243], v147 offset:36928
	s_waitcnt lgkmcnt(4)
;     ...
;     for (int ks = 0; ks < 4; ++ks) {
;       bf16x8 wf[2], xf[4];
; #pragma unroll
;       for (int ct = 0; ct < 2; ++ct) wf[ct] = *(const bf16x8*)(bs + ct * 32 * LD + ks * 16);
; #pragma unroll
;       for (int tt = 0; tt < 4; ++tt) xf[tt] = *(const bf16x8*)(as + tt * 32 * LD + ks * 16);
; #pragma unroll
;       for (int ct = 0; ct < 2; ++ct)
; #pragma unroll
;         for (int tt = 0; tt < 4; ++tt) acc[ct][tt] = __builtin_amdgcn_mfma_f32_32x32x16_bf16(wf[ct], xf[tt], acc[ct][tt], 0, 0, 0);
;     }
;     __builtin_amdgcn_sched_barrier(0);
;   }
; __device__ void phase_gemm2(const Params& p, char* lds, int bid, int nb, bool fused) {
;     ...
;       for (int tt = 0; tt < 4; ++tt) {
;         const int tok = m0 + wr * 128 + tt * 32 + l31;
;         const float* xr = p.x + (size_t)tok * DM + n0 + wc * 64;
;         float ss = 0.f;
; #pragma unroll
;         for (int ct = 0; ct < 2; ++ct)
; #pragma unroll
;           for (int rq = 0; rq < 4; ++rq) {
;             const f32x4 xv = *(const f32x4*)(xr + ct * 32 + 8 * rq + 4 * h);
; #pragma unroll
;             for (int e = 0; e < 4; ++e) { acc[ct][tt][rq * 4 + e] += xv[e]; ss += acc[ct][tt][rq * 4 + e] * acc[ct][tt][rq * 4 + e]; }
;           }
;         ss += __shfl_xor(ss, 32);
;         olds[tt] = 0.f;
;         if (h == 0) olds[tt] = atomicAdd(p.ssq + tok, ss);
;       }
	v_mfma_f32_32x32x16_bf16 v[82:97], v[216:219], v[228:231], v[82:97]
	ds_read_b128 v[212:215], v148 offset:41536
	v_mfma_f32_32x32x16_bf16 v[66:81], v[224:227], v[228:231], v[66:81]
	ds_read_b128 v[244:247], v147 offset:41536
	s_waitcnt lgkmcnt(5)
	v_mfma_f32_32x32x16_bf16 v[50:65], v[216:219], v[232:235], v[50:65]
	ds_read_b128 v[228:231], v147 offset:46144
	v_mfma_f32_32x32x16_bf16 v[34:49], v[224:227], v[232:235], v[34:49]
	s_waitcnt lgkmcnt(5)
	v_mfma_f32_32x32x16_bf16 v[18:33], v[216:219], v[236:239], v[18:33]
	ds_read_b128 v[232:235], v147 offset:50752
	v_mfma_f32_32x32x16_bf16 v[2:17], v[224:227], v[236:239], v[2:17]
	s_waitcnt lgkmcnt(4)
	v_mfma_f32_32x32x16_bf16 v[98:113], v[208:211], v[240:243], v[98:113]
	ds_read_b128 v[216:219], v148 offset:36960
	s_waitcnt lgkmcnt(4)
	v_mfma_f32_32x32x16_bf16 v[114:129], v[212:215], v[240:243], v[114:129]
	ds_read_b128 v[236:239], v147 offset:36960
	s_waitcnt lgkmcnt(4)
	v_mfma_f32_32x32x16_bf16 v[82:97], v[208:211], v[244:247], v[82:97]
	ds_read_b128 v[224:227], v148 offset:41568
	v_mfma_f32_32x32x16_bf16 v[66:81], v[212:215], v[244:247], v[66:81]
	ds_read_b128 v[240:243], v147 offset:41568
	s_waitcnt lgkmcnt(5)
	v_mfma_f32_32x32x16_bf16 v[50:65], v[208:211], v[228:231], v[50:65]
	ds_read_b128 v[244:247], v147 offset:46176
	v_mfma_f32_32x32x16_bf16 v[34:49], v[212:215], v[228:231], v[34:49]
	s_waitcnt lgkmcnt(5)
	v_mfma_f32_32x32x16_bf16 v[18:33], v[208:211], v[232:235], v[18:33]
	ds_read_b128 v[228:231], v147 offset:50784
	v_mfma_f32_32x32x16_bf16 v[2:17], v[212:215], v[232:235], v[2:17]
	s_waitcnt lgkmcnt(4)
	v_mfma_f32_32x32x16_bf16 v[98:113], v[216:219], v[236:239], v[98:113]
	s_waitcnt lgkmcnt(3)
	v_mfma_f32_32x32x16_bf16 v[114:129], v[224:227], v[236:239], v[114:129]
	s_waitcnt lgkmcnt(2)
	v_mfma_f32_32x32x16_bf16 v[82:97], v[216:219], v[240:243], v[82:97]
	v_mfma_f32_32x32x16_bf16 v[66:81], v[224:227], v[240:243], v[66:81]
	s_waitcnt lgkmcnt(1)
	v_mfma_f32_32x32x16_bf16 v[50:65], v[216:219], v[244:247], v[50:65]
	v_mfma_f32_32x32x16_bf16 v[34:49], v[224:227], v[244:247], v[34:49]
	s_waitcnt lgkmcnt(0)
	v_mfma_f32_32x32x16_bf16 v[18:33], v[216:219], v[228:231], v[18:33]
	v_mfma_f32_32x32x16_bf16 v[2:17], v[224:227], v[228:231], v[2:17]
	s_andn2_b64 vcc, exec, s[12:13]
	s_cbranch_vccnz .Lp5_slow
	v_or_b32_e32 v130, s38, v146
	v_add_u32_e32 v152, s5, v130
	s_lshl_b32 s14, s4, 2
	s_lshl_b32 s36, s34, 2
	s_add_i32 s36, s36, s14
	v_lshl_add_u32 v162, v152, 12, v150
	v_lshlrev_b32_e32 v163, 2, v152
	s_add_u32 s54, s24, s36
	s_addc_u32 s55, s25, 0
	s_add_u32 s56, s54, 0x20000
	s_addc_u32 s57, s55, 0
	s_add_u32 s58, s54, 0x40000
	s_addc_u32 s59, s55, 0
	s_add_u32 s60, s54, 0x60000
	s_addc_u32 s61, s55, 0
	global_load_dwordx4 v[164:167], v162, s[54:55]
	global_load_dwordx4 v[168:171], v162, s[54:55] offset:32
	global_load_dwordx4 v[172:175], v162, s[54:55] offset:64
	global_load_dwordx4 v[176:179], v162, s[54:55] offset:96
	global_load_dwordx4 v[180:183], v162, s[54:55] offset:128
	global_load_dwordx4 v[184:187], v162, s[54:55] offset:160
	global_load_dwordx4 v[188:191], v162, s[54:55] offset:192
	global_load_dwordx4 v[192:195], v162, s[54:55] offset:224
	global_load_dwordx4 v[224:227], v162, s[56:57]
	global_load_dwordx4 v[228:231], v162, s[56:57] offset:32
	global_load_dwordx4 v[232:235], v162, s[56:57] offset:64
	global_load_dwordx4 v[236:239], v162, s[56:57] offset:96
	global_load_dwordx4 v[240:243], v162, s[56:57] offset:128
	global_load_dwordx4 v[244:247], v162, s[56:57] offset:160
	global_load_dwordx4 v[248:251], v162, s[56:57] offset:192
	global_load_dwordx4 v[252:255], v162, s[56:57] offset:224
	global_load_dwordx4 v[196:199], v162, s[58:59]
	global_load_dwordx4 v[200:203], v162, s[58:59] offset:32
	global_load_dwordx4 v[204:207], v162, s[58:59] offset:64
	global_load_dwordx4 v[208:211], v162, s[58:59] offset:96
	global_load_dwordx4 v[212:215], v162, s[58:59] offset:128
	global_load_dwordx4 v[216:219], v162, s[58:59] offset:160
	global_load_dwordx4 v[130:133], v162, s[58:59] offset:192
	global_load_dwordx4 v[134:137], v162, s[58:59] offset:224
	v_mbcnt_lo_u32_b32 v160, -1, 0
	v_mbcnt_hi_u32_b32 v160, -1, v160
	v_xor_b32_e32 v160, 32, v160
	v_lshlrev_b32_e32 v160, 2, v160
	v_cmp_eq_u32_e64 s[62:63], 0, v159
	s_add_u32 s66, s8, s36
	s_addc_u32 s67, s9, 0
	s_waitcnt vmcnt(16)
	v_pk_add_f32 v[98:99], v[98:99], v[164:165]
	v_pk_add_f32 v[100:101], v[100:101], v[166:167]
	v_pk_add_f32 v[102:103], v[102:103], v[168:169]
	v_pk_add_f32 v[104:105], v[104:105], v[170:171]
	v_pk_add_f32 v[106:107], v[106:107], v[172:173]
	v_pk_add_f32 v[108:109], v[108:109], v[174:175]
	v_pk_add_f32 v[110:111], v[110:111], v[176:177]
	v_pk_add_f32 v[112:113], v[112:113], v[178:179]
	v_pk_add_f32 v[114:115], v[114:115], v[180:181]
	v_pk_add_f32 v[116:117], v[116:117], v[182:183]
	v_pk_add_f32 v[118:119], v[118:119], v[184:185]
	v_pk_add_f32 v[120:121], v[120:121], v[186:187]
	v_pk_add_f32 v[122:123], v[122:123], v[188:189]
	v_pk_add_f32 v[124:125], v[124:125], v[190:191]
	v_pk_add_f32 v[126:127], v[126:127], v[192:193]
	v_pk_add_f32 v[128:129], v[128:129], v[194:195]
	v_pk_mul_f32 v[146:147], v[98:99], v[98:99]
	v_add_f32_e32 v161, v146, v147
	v_pk_mul_f32 v[148:149], v[100:101], v[100:101]
	v_add_f32_e32 v161, v148, v161
	v_add_f32_e32 v161, v149, v161
	v_pk_mul_f32 v[146:147], v[102:103], v[102:103]
	v_add_f32_e32 v161, v146, v161
	v_add_f32_e32 v161, v147, v161
	v_pk_mul_f32 v[148:149], v[104:105], v[104:105]
	v_add_f32_e32 v161, v148, v161
	v_add_f32_e32 v161, v149, v161
	v_pk_mul_f32 v[146:147], v[106:107], v[106:107]
	v_add_f32_e32 v161, v146, v161
	v_add_f32_e32 v161, v147, v161
	v_pk_mul_f32 v[148:149], v[108:109], v[108:109]
	v_add_f32_e32 v161, v148, v161
	v_add_f32_e32 v161, v149, v161
	v_pk_mul_f32 v[146:147], v[110:111], v[110:111]
	v_add_f32_e32 v161, v146, v161
	v_add_f32_e32 v161, v147, v161
	v_pk_mul_f32 v[148:149], v[112:113], v[112:113]
	v_add_f32_e32 v161, v148, v161
	v_add_f32_e32 v161, v149, v161
	v_pk_mul_f32 v[146:147], v[114:115], v[114:115]
	v_add_f32_e32 v161, v146, v161
	v_add_f32_e32 v161, v147, v161
	v_pk_mul_f32 v[148:149], v[116:117], v[116:117]
	v_add_f32_e32 v161, v148, v161
	v_add_f32_e32 v161, v149, v161
	v_pk_mul_f32 v[146:147], v[118:119], v[118:119]
	v_add_f32_e32 v161, v146, v161
	v_add_f32_e32 v161, v147, v161
	v_pk_mul_f32 v[148:149], v[120:121], v[120:121]
	v_add_f32_e32 v161, v148, v161
	v_add_f32_e32 v161, v149, v161
	v_pk_mul_f32 v[146:147], v[122:123], v[122:123]
	v_add_f32_e32 v161, v146, v161
	v_add_f32_e32 v161, v147, v161
	v_pk_mul_f32 v[148:149], v[124:125], v[124:125]
	v_add_f32_e32 v161, v148, v161
	v_add_f32_e32 v161, v149, v161
	v_pk_mul_f32 v[146:147], v[126:127], v[126:127]
	v_add_f32_e32 v161, v146, v161
	v_add_f32_e32 v161, v147, v161
	v_pk_mul_f32 v[148:149], v[128:129], v[128:129]
	v_add_f32_e32 v161, v148, v161
	v_add_f32_e32 v161, v149, v161
	ds_bpermute_b32 v146, v160, v161
	s_waitcnt lgkmcnt(0)
; __device__ void phase_gemm2(const Params& p, char* lds, int bid, int nb, bool fused) {
;     ...
;       for (int tt = 0; tt < 4; ++tt) {
;         const int tok = m0 + wr * 128 + tt * 32 + l31;
;         const float* xr = p.x + (size_t)tok * DM + n0 + wc * 64;
;         float ss = 0.f;
; #pragma unroll
;         for (int ct = 0; ct < 2; ++ct)
; #pragma unroll
;           for (int rq = 0; rq < 4; ++rq) {
;             const f32x4 xv = *(const f32x4*)(xr + ct * 32 + 8 * rq + 4 * h);
; #pragma unroll
;             for (int e = 0; e < 4; ++e) { acc[ct][tt][rq * 4 + e] += xv[e]; ss += acc[ct][tt][rq * 4 + e] * acc[ct][tt][rq * 4 + e]; }
;           }
;         ss += __shfl_xor(ss, 32);
;         olds[tt] = 0.f;
;         if (h == 0) olds[tt] = atomicAdd(p.ssq + tok, ss);
;       }
;     ...
;         const float* gr = p.final_gain + n0 + wc * 64;
; #pragma unroll
;         for (int ct = 0; ct < 2; ++ct)
; #pragma unroll
;           for (int rq = 0; rq < 4; ++rq) {
;             const int c = ct * 32 + 8 * rq + 4 * h;
;             f32x4 o;
;             if (fused) {
;               const f32x4 gv = *(const f32x4*)(gr + c);
	v_add_f32_e32 v161, v161, v146
	s_and_saveexec_b64 s[64:65], s[62:63]
	global_atomic_add_f32 v139, v163, v161, s[18:19] sc0
	s_or_b64 exec, exec, s[64:65]
	global_load_dwordx4 v[164:167], v162, s[60:61]
	global_load_dwordx4 v[168:171], v162, s[60:61] offset:32
	global_load_dwordx4 v[172:175], v162, s[60:61] offset:64
	global_load_dwordx4 v[176:179], v162, s[60:61] offset:96
	global_load_dwordx4 v[180:183], v162, s[60:61] offset:128
	global_load_dwordx4 v[184:187], v162, s[60:61] offset:160
	global_load_dwordx4 v[188:191], v162, s[60:61] offset:192
	global_load_dwordx4 v[192:195], v162, s[60:61] offset:224
	s_waitcnt vmcnt(17)
	v_pk_add_f32 v[82:83], v[82:83], v[224:225]
	v_pk_add_f32 v[84:85], v[84:85], v[226:227]
	v_pk_add_f32 v[86:87], v[86:87], v[228:229]
	v_pk_add_f32 v[88:89], v[88:89], v[230:231]
	v_pk_add_f32 v[90:91], v[90:91], v[232:233]
	v_pk_add_f32 v[92:93], v[92:93], v[234:235]
	v_pk_add_f32 v[94:95], v[94:95], v[236:237]
	v_pk_add_f32 v[96:97], v[96:97], v[238:239]
	v_pk_add_f32 v[66:67], v[66:67], v[240:241]
	v_pk_add_f32 v[68:69], v[68:69], v[242:243]
	v_pk_add_f32 v[70:71], v[70:71], v[244:245]
	v_pk_add_f32 v[72:73], v[72:73], v[246:247]
	v_pk_add_f32 v[74:75], v[74:75], v[248:249]
	v_pk_add_f32 v[76:77], v[76:77], v[250:251]
	v_pk_add_f32 v[78:79], v[78:79], v[252:253]
	v_pk_add_f32 v[80:81], v[80:81], v[254:255]
	v_pk_mul_f32 v[146:147], v[82:83], v[82:83]
	v_add_f32_e32 v220, v146, v147
	v_pk_mul_f32 v[148:149], v[84:85], v[84:85]
	v_add_f32_e32 v220, v148, v220
	v_add_f32_e32 v220, v149, v220
	v_pk_mul_f32 v[146:147], v[86:87], v[86:87]
	v_add_f32_e32 v220, v146, v220
	v_add_f32_e32 v220, v147, v220
	v_pk_mul_f32 v[148:149], v[88:89], v[88:89]
	v_add_f32_e32 v220, v148, v220
	v_add_f32_e32 v220, v149, v220
	v_pk_mul_f32 v[146:147], v[90:91], v[90:91]
	v_add_f32_e32 v220, v146, v220
	v_add_f32_e32 v220, v147, v220
	v_pk_mul_f32 v[148:149], v[92:93], v[92:93]
	v_add_f32_e32 v220, v148, v220
	v_add_f32_e32 v220, v149, v220
	v_pk_mul_f32 v[146:147], v[94:95], v[94:95]
	v_add_f32_e32 v220, v146, v220
	v_add_f32_e32 v220, v147, v220
	v_pk_mul_f32 v[148:149], v[96:97], v[96:97]
	v_add_f32_e32 v220, v148, v220
	v_add_f32_e32 v220, v149, v220
	v_pk_mul_f32 v[146:147], v[66:67], v[66:67]
	v_add_f32_e32 v220, v146, v220
	v_add_f32_e32 v220, v147, v220
	v_pk_mul_f32 v[148:149], v[68:69], v[68:69]
	v_add_f32_e32 v220, v148, v220
	v_add_f32_e32 v220, v149, v220
	v_pk_mul_f32 v[146:147], v[70:71], v[70:71]
	v_add_f32_e32 v220, v146, v220
	v_add_f32_e32 v220, v147, v220
	v_pk_mul_f32 v[148:149], v[72:73], v[72:73]
	v_add_f32_e32 v220, v148, v220
	v_add_f32_e32 v220, v149, v220
	v_pk_mul_f32 v[146:147], v[74:75], v[74:75]
	v_add_f32_e32 v220, v146, v220
	v_add_f32_e32 v220, v147, v220
	v_pk_mul_f32 v[148:149], v[76:77], v[76:77]
	v_add_f32_e32 v220, v148, v220
	v_add_f32_e32 v220, v149, v220
	v_pk_mul_f32 v[146:147], v[78:79], v[78:79]
	v_add_f32_e32 v220, v146, v220
	v_add_f32_e32 v220, v147, v220
	v_pk_mul_f32 v[148:149], v[80:81], v[80:81]
	v_add_f32_e32 v220, v148, v220
	v_add_f32_e32 v220, v149, v220
	ds_bpermute_b32 v146, v160, v220
	s_waitcnt lgkmcnt(0)
	v_add_f32_e32 v220, v220, v146
	s_and_saveexec_b64 s[64:65], s[62:63]
	global_atomic_add_f32 v141, v163, v220, s[18:19] offset:128 sc0
	s_or_b64 exec, exec, s[64:65]
	global_load_dwordx4 v[224:227], v150, s[66:67]
	global_load_dwordx4 v[228:231], v150, s[66:67] offset:32
	global_load_dwordx4 v[232:235], v150, s[66:67] offset:64
	global_load_dwordx4 v[236:239], v150, s[66:67] offset:96
	global_load_dwordx4 v[240:243], v150, s[66:67] offset:128
	global_load_dwordx4 v[244:247], v150, s[66:67] offset:160
	global_load_dwordx4 v[248:251], v150, s[66:67] offset:192
	global_load_dwordx4 v[252:255], v150, s[66:67] offset:224
	s_waitcnt vmcnt(18)
; __device__ void phase_gemm2(const Params& p, char* lds, int bid, int nb, bool fused) {
;     ...
;       for (int tt = 0; tt < 4; ++tt) {
;         const int tok = m0 + wr * 128 + tt * 32 + l31;
;         const float* xr = p.x + (size_t)tok * DM + n0 + wc * 64;
;         float ss = 0.f;
; #pragma unroll
;         for (int ct = 0; ct < 2; ++ct)
; #pragma unroll
;           for (int rq = 0; rq < 4; ++rq) {
;             const f32x4 xv = *(const f32x4*)(xr + ct * 32 + 8 * rq + 4 * h);
; #pragma unroll
;             for (int e = 0; e < 4; ++e) { acc[ct][tt][rq * 4 + e] += xv[e]; ss += acc[ct][tt][rq * 4 + e] * acc[ct][tt][rq * 4 + e]; }
;           }
;         ss += __shfl_xor(ss, 32);
;         olds[tt] = 0.f;
;         if (h == 0) olds[tt] = atomicAdd(p.ssq + tok, ss);
;       }
;       asm volatile("" :: "v"(olds[0]), "v"(olds[1]), "v"(olds[2]), "v"(olds[3]));
;       if (fused) {
;         __syncthreads();
;         if (threadIdx.x == 0) {
;           __hip_atomic_fetch_add(p.pcnt + (m0 >> 8), 1, __ATOMIC_RELAXED, __HIP_MEMORY_SCOPE_AGENT);
;           while (__hip_atomic_load(p.pcnt + (m0 >> 8), __ATOMIC_RELAXED, __HIP_MEMORY_SCOPE_AGENT) < NNT) __builtin_amdgcn_s_sleep(2);
;         }
	v_pk_add_f32 v[50:51], v[50:51], v[196:197]
	v_pk_add_f32 v[52:53], v[52:53], v[198:199]
	v_pk_add_f32 v[54:55], v[54:55], v[200:201]
	v_pk_add_f32 v[56:57], v[56:57], v[202:203]
	v_pk_add_f32 v[58:59], v[58:59], v[204:205]
	v_pk_add_f32 v[60:61], v[60:61], v[206:207]
	v_pk_add_f32 v[62:63], v[62:63], v[208:209]
	v_pk_add_f32 v[64:65], v[64:65], v[210:211]
	v_pk_add_f32 v[34:35], v[34:35], v[212:213]
	v_pk_add_f32 v[36:37], v[36:37], v[214:215]
	v_pk_add_f32 v[38:39], v[38:39], v[216:217]
	v_pk_add_f32 v[40:41], v[40:41], v[218:219]
	v_pk_add_f32 v[42:43], v[42:43], v[130:131]
	v_pk_add_f32 v[44:45], v[44:45], v[132:133]
	v_pk_add_f32 v[46:47], v[46:47], v[134:135]
	v_pk_add_f32 v[48:49], v[48:49], v[136:137]
	v_pk_mul_f32 v[146:147], v[50:51], v[50:51]
	v_add_f32_e32 v221, v146, v147
	v_pk_mul_f32 v[148:149], v[52:53], v[52:53]
	v_add_f32_e32 v221, v148, v221
	v_add_f32_e32 v221, v149, v221
	v_pk_mul_f32 v[146:147], v[54:55], v[54:55]
	v_add_f32_e32 v221, v146, v221
	v_add_f32_e32 v221, v147, v221
	v_pk_mul_f32 v[148:149], v[56:57], v[56:57]
	v_add_f32_e32 v221, v148, v221
	v_add_f32_e32 v221, v149, v221
	v_pk_mul_f32 v[146:147], v[58:59], v[58:59]
	v_add_f32_e32 v221, v146, v221
	v_add_f32_e32 v221, v147, v221
	v_pk_mul_f32 v[148:149], v[60:61], v[60:61]
	v_add_f32_e32 v221, v148, v221
	v_add_f32_e32 v221, v149, v221
	v_pk_mul_f32 v[146:147], v[62:63], v[62:63]
	v_add_f32_e32 v221, v146, v221
	v_add_f32_e32 v221, v147, v221
	v_pk_mul_f32 v[148:149], v[64:65], v[64:65]
	v_add_f32_e32 v221, v148, v221
	v_add_f32_e32 v221, v149, v221
	v_pk_mul_f32 v[146:147], v[34:35], v[34:35]
	v_add_f32_e32 v221, v146, v221
	v_add_f32_e32 v221, v147, v221
	v_pk_mul_f32 v[148:149], v[36:37], v[36:37]
	v_add_f32_e32 v221, v148, v221
	v_add_f32_e32 v221, v149, v221
	v_pk_mul_f32 v[146:147], v[38:39], v[38:39]
	v_add_f32_e32 v221, v146, v221
	v_add_f32_e32 v221, v147, v221
	v_pk_mul_f32 v[148:149], v[40:41], v[40:41]
	v_add_f32_e32 v221, v148, v221
	v_add_f32_e32 v221, v149, v221
	v_pk_mul_f32 v[146:147], v[42:43], v[42:43]
	v_add_f32_e32 v221, v146, v221
	v_add_f32_e32 v221, v147, v221
	v_pk_mul_f32 v[148:149], v[44:45], v[44:45]
	v_add_f32_e32 v221, v148, v221
	v_add_f32_e32 v221, v149, v221
	v_pk_mul_f32 v[146:147], v[46:47], v[46:47]
	v_add_f32_e32 v221, v146, v221
	v_add_f32_e32 v221, v147, v221
	v_pk_mul_f32 v[148:149], v[48:49], v[48:49]
	v_add_f32_e32 v221, v148, v221
	v_add_f32_e32 v221, v149, v221
	ds_bpermute_b32 v146, v160, v221
	s_waitcnt lgkmcnt(0)
	v_add_f32_e32 v221, v221, v146
	s_and_saveexec_b64 s[64:65], s[62:63]
	global_atomic_add_f32 v143, v163, v221, s[18:19] offset:256 sc0
	s_or_b64 exec, exec, s[64:65]
	s_waitcnt vmcnt(10)
	v_pk_add_f32 v[18:19], v[18:19], v[164:165]
	v_pk_add_f32 v[20:21], v[20:21], v[166:167]
	v_pk_add_f32 v[22:23], v[22:23], v[168:169]
	v_pk_add_f32 v[24:25], v[24:25], v[170:171]
	v_pk_add_f32 v[26:27], v[26:27], v[172:173]
	v_pk_add_f32 v[28:29], v[28:29], v[174:175]
	v_pk_add_f32 v[30:31], v[30:31], v[176:177]
	v_pk_add_f32 v[32:33], v[32:33], v[178:179]
	v_pk_add_f32 v[2:3], v[2:3], v[180:181]
	v_pk_add_f32 v[4:5], v[4:5], v[182:183]
	v_pk_add_f32 v[6:7], v[6:7], v[184:185]
	v_pk_add_f32 v[8:9], v[8:9], v[186:187]
	v_pk_add_f32 v[10:11], v[10:11], v[188:189]
	v_pk_add_f32 v[12:13], v[12:13], v[190:191]
	v_pk_add_f32 v[14:15], v[14:15], v[192:193]
	v_pk_add_f32 v[16:17], v[16:17], v[194:195]
	v_pk_mul_f32 v[146:147], v[18:19], v[18:19]
	v_add_f32_e32 v222, v146, v147
	v_pk_mul_f32 v[148:149], v[20:21], v[20:21]
	v_add_f32_e32 v222, v148, v222
	v_add_f32_e32 v222, v149, v222
	v_pk_mul_f32 v[146:147], v[22:23], v[22:23]
	v_add_f32_e32 v222, v146, v222
	v_add_f32_e32 v222, v147, v222
	v_pk_mul_f32 v[148:149], v[24:25], v[24:25]
	v_add_f32_e32 v222, v148, v222
	v_add_f32_e32 v222, v149, v222
	v_pk_mul_f32 v[146:147], v[26:27], v[26:27]
	v_add_f32_e32 v222, v146, v222
	v_add_f32_e32 v222, v147, v222
	v_pk_mul_f32 v[148:149], v[28:29], v[28:29]
	v_add_f32_e32 v222, v148, v222
	v_add_f32_e32 v222, v149, v222
	v_pk_mul_f32 v[146:147], v[30:31], v[30:31]
	v_add_f32_e32 v222, v146, v222
	v_add_f32_e32 v222, v147, v222
	v_pk_mul_f32 v[148:149], v[32:33], v[32:33]
	v_add_f32_e32 v222, v148, v222
	v_add_f32_e32 v222, v149, v222
	v_pk_mul_f32 v[146:147], v[2:3], v[2:3]
	v_add_f32_e32 v222, v146, v222
	v_add_f32_e32 v222, v147, v222
	v_pk_mul_f32 v[148:149], v[4:5], v[4:5]
	v_add_f32_e32 v222, v148, v222
	v_add_f32_e32 v222, v149, v222
	v_pk_mul_f32 v[146:147], v[6:7], v[6:7]
	v_add_f32_e32 v222, v146, v222
	v_add_f32_e32 v222, v147, v222
	v_pk_mul_f32 v[148:149], v[8:9], v[8:9]
	v_add_f32_e32 v222, v148, v222
	v_add_f32_e32 v222, v149, v222
	v_pk_mul_f32 v[146:147], v[10:11], v[10:11]
	v_add_f32_e32 v222, v146, v222
	v_add_f32_e32 v222, v147, v222
	v_pk_mul_f32 v[148:149], v[12:13], v[12:13]
	v_add_f32_e32 v222, v148, v222
	v_add_f32_e32 v222, v149, v222
	v_pk_mul_f32 v[146:147], v[14:15], v[14:15]
	v_add_f32_e32 v222, v146, v222
	v_add_f32_e32 v222, v147, v222
	v_pk_mul_f32 v[148:149], v[16:17], v[16:17]
	v_add_f32_e32 v222, v148, v222
	v_add_f32_e32 v222, v149, v222
	ds_bpermute_b32 v146, v160, v222
	s_waitcnt lgkmcnt(0)
	v_add_f32_e32 v222, v222, v146
	s_and_saveexec_b64 s[64:65], s[62:63]
	global_atomic_add_f32 v145, v163, v222, s[18:19] offset:384 sc0
	s_or_b64 exec, exec, s[64:65]
	s_waitcnt vmcnt(0)
	s_barrier
	s_and_saveexec_b64 s[64:65], s[48:49]
	s_cbranch_execz .Lp5_pollend
	s_ashr_i32 s38, s38, 8
	s_mov_b64 s[40:41], exec
	s_ashr_i32 s39, s38, 31
	s_lshl_b64 s[38:39], s[38:39], 2
	v_mbcnt_lo_u32_b32 v146, s40, 0
	s_add_u32 s38, s20, s38
	v_mbcnt_hi_u32_b32 v146, s41, v146
	s_addc_u32 s39, s21, s39
	v_cmp_eq_u32_e32 vcc, 0, v146
	s_and_saveexec_b64 s[42:43], vcc
	s_cbranch_execz .Lp5_noinc
	s_bcnt1_i32_b64 s40, s[40:41]
	v_mov_b32_e32 v146, s40
	global_atomic_add v151, v146, s[38:39]

; #define LAS __attribute__((address_space(3)))
; __global__ void __launch_bounds__(NT) fwd_mega(Params p) {
;   cg::grid_group grid = cg::this_grid();
;   const int bid = blockIdx.x, nb = gridDim.x;
;   volatile LAS unsigned* xst = (volatile LAS unsigned*)(dyn_lds + LDS_BYTES - 32);
;   if (threadIdx.x == 0) { xst[0] = 0u; xst[1] = 0u; }
;   __syncthreads();
;   const XcdBarrier xb = xcd_barrier_post(p.xbar, xst);
;   phase_prep(p, dyn_lds, bid, nb);
;   xcd_barrier(xb);
;     ...
;   phase_gemm1(p, dyn_lds, bid, nb, REP - 6);
;   xcd_barrier(xb);
;     ...
;   phase_gemm1(p, dyn_lds, bid, nb);
;     ...
;   xcd_barrier(xb);
;   phase_gemm1(p, dyn_lds, bid, nb);
;     ...
;   xcd_barrier(xb);
;   phase_mix(p, dyn_lds, bid, nb);
;     ...
;   __syncthreads();
;   phase_prep_only(p, dyn_lds, bid, nb);
;     ...
;   xcd_barrier(xb);
;   phase_scan(p, bid, nb);
;     ...
;   xcd_barrier(xb);
;     ...
;   phase_scan(p, bid, nb);
;   phase_scan(p, bid, nb);
;   phase_scan(p, bid, nb);
;   phase_scan(p, bid, nb);
;     ...
;   phase_attn_queue(p, dyn_lds, bid, nb);
;   xcd_barrier(xb);
;   phase_rwkv_out(p, bid, nb);
;   xcd_barrier(xb);
;   const bool fused = (nb & 31) == 0;
;   phase_gemm2(p, dyn_lds, bid, nb, fused);
;   if (!fused) {
;     grid.sync();
;     phase_final(p, bid, nb);
;   }
; }
	.amdhsa_kernel _Z8fwd_mega6Params
		.amdhsa_group_segment_fixed_size 0
		.amdhsa_private_segment_fixed_size 0
		.amdhsa_kernarg_size 592
		.amdhsa_user_sgpr_count 2
		.amdhsa_user_sgpr_dispatch_ptr 0
		.amdhsa_user_sgpr_queue_ptr 0
		.amdhsa_user_sgpr_kernarg_segment_ptr 1
		.amdhsa_user_sgpr_dispatch_id 0
		.amdhsa_user_sgpr_kernarg_preload_length 0
		.amdhsa_user_sgpr_kernarg_preload_offset 0
		.amdhsa_user_sgpr_private_segment_size 0
		.amdhsa_uses_dynamic_stack 0
		.amdhsa_enable_private_segment 0
		.amdhsa_system_sgpr_workgroup_id_x 1
		.amdhsa_system_sgpr_workgroup_id_y 0
		.amdhsa_system_sgpr_workgroup_id_z 0
		.amdhsa_system_sgpr_workgroup_info 0
		.amdhsa_system_vgpr_workitem_id 2
		.amdhsa_next_free_vgpr 256
		.amdhsa_next_free_sgpr 96
		.amdhsa_accum_offset 256
		.amdhsa_reserve_vcc 1
		.amdhsa_float_round_mode_32 0
		.amdhsa_float_round_mode_16_64 0
		.amdhsa_float_denorm_mode_32 3
		.amdhsa_float_denorm_mode_16_64 3
		.amdhsa_dx10_clamp 1
		.amdhsa_ieee_mode 1
		.amdhsa_fp16_overflow 0
		.amdhsa_tg_split 0
		.amdhsa_exception_fp_ieee_invalid_op 0
		.amdhsa_exception_fp_denorm_src 0
		.amdhsa_exception_fp_ieee_div_zero 0
		.amdhsa_exception_fp_ieee_overflow 0
		.amdhsa_exception_fp_ieee_underflow 0
		.amdhsa_exception_fp_ieee_inexact 0
		.amdhsa_exception_int_div_zero 0
	.end_amdhsa_kernel

; #define LAS __attribute__((address_space(3)))
; __global__ void __launch_bounds__(NT) fwd_mega(Params p) {
;   cg::grid_group grid = cg::this_grid();
;   const int bid = blockIdx.x, nb = gridDim.x;
;   volatile LAS unsigned* xst = (volatile LAS unsigned*)(dyn_lds + LDS_BYTES - 32);
;   if (threadIdx.x == 0) { xst[0] = 0u; xst[1] = 0u; }
;   __syncthreads();
;   const XcdBarrier xb = xcd_barrier_post(p.xbar, xst);
;   phase_prep(p, dyn_lds, bid, nb);
;   xcd_barrier(xb);
;     ...
;   phase_gemm1(p, dyn_lds, bid, nb, REP - 6);
;   xcd_barrier(xb);
;     ...
;   phase_gemm1(p, dyn_lds, bid, nb);
;     ...
;   xcd_barrier(xb);
;   phase_gemm1(p, dyn_lds, bid, nb);
;     ...
;   xcd_barrier(xb);
;   phase_mix(p, dyn_lds, bid, nb);
;     ...
;   __syncthreads();
;   phase_prep_only(p, dyn_lds, bid, nb);
;     ...
;   xcd_barrier(xb);
;   phase_scan(p, bid, nb);
;     ...
;   xcd_barrier(xb);
;     ...
;   phase_scan(p, bid, nb);
;   phase_scan(p, bid, nb);
;   phase_scan(p, bid, nb);
;   phase_scan(p, bid, nb);
;     ...
;   phase_attn_queue(p, dyn_lds, bid, nb);
;   xcd_barrier(xb);
;   phase_rwkv_out(p, bid, nb);
;   xcd_barrier(xb);
;   const bool fused = (nb & 31) == 0;
;   phase_gemm2(p, dyn_lds, bid, nb, fused);
;   if (!fused) {
;     grid.sync();
;     phase_final(p, bid, nb);
;   }
; }
amdhsa.kernels:
  - .agpr_count:     0
    .args:
      - .offset:         0
        .size:           336
        .value_kind:     by_value
      - .offset:         336
        .size:           4
        .value_kind:     hidden_block_count_x
      - .offset:         340
        .size:           4
        .value_kind:     hidden_block_count_y
      - .offset:         344
        .size:           4
        .value_kind:     hidden_block_count_z
      - .offset:         348
        .size:           2
        .value_kind:     hidden_group_size_x
      - .offset:         350
        .size:           2
        .value_kind:     hidden_group_size_y
      - .offset:         352
        .size:           2
        .value_kind:     hidden_group_size_z
      - .offset:         354
        .size:           2
        .value_kind:     hidden_remainder_x
      - .offset:         356
        .size:           2
        .value_kind:     hidden_remainder_y
      - .offset:         358
        .size:           2
        .value_kind:     hidden_remainder_z
      - .offset:         376
        .size:           8
        .value_kind:     hidden_global_offset_x
      - .offset:         384
        .size:           8
        .value_kind:     hidden_global_offset_y
      - .offset:         392
        .size:           8
        .value_kind:     hidden_global_offset_z
      - .offset:         400
        .size:           2
        .value_kind:     hidden_grid_dims
      - .offset:         424
        .size:           8
        .value_kind:     hidden_multigrid_sync_arg
      - .offset:         456
        .size:           4
        .value_kind:     hidden_dynamic_lds_size
    .group_segment_fixed_size: 0
    .kernarg_segment_align: 8
    .kernarg_segment_size: 592
    .language:       OpenCL C
    .language_version:
      - 2
      - 0
    .max_flat_workgroup_size: 512
    .name:           _Z8fwd_mega6Params
    .private_segment_fixed_size: 0
    .sgpr_count:     102
    .sgpr_spill_count: 0
    .symbol:         _Z8fwd_mega6Params.kd
    .uniform_work_group_size: 1
    .uses_dynamic_stack: false
    .vgpr_count:     256
    .vgpr_spill_count: 0
    .wavefront_size: 64
